# MLA: skip fully-masked diagonal wave-tiles (drone path), skip useless next-tile QK on last iteration; resid epilogue flat->global with counted vmcnt
# speedup vs baseline: 1.0051x; 1.0051x over previous
; template <int DQ, int DK1, int DV, int MODE> ...
;     ...
;             const bool diag = (64 * kt + 63 > q0w) || (MODE == 2 && 64 * kt <= q0w + 31 - 128);
;             if (diag) {
; #pragma unroll
;                 for (int i = 0; i < 16; ++i) { const int key = 64 * kt + (i & 3) + 8 * (i >> 2) + 4 * hi;
;                     bool ok0 = key <= qpos, ok1 = key + 32 <= qpos;
;                     if (MODE == 2) { ok0 = ok0 && key > qpos - 128; ok1 = ok1 && key + 32 > qpos - 128; }
;                     if (!ok0) p0[i] = -INFINITY; if (!ok1) p1[i] = -INFINITY; }
.LBB0_425:
	s_add_i32 s48, s86, 31
	s_cmp_gt_i32 s40, s48
	s_cbranch_scc1 .Lmla_drone
	s_add_i32 s48, s40, 63
	s_cmp_le_i32 s48, s86
	s_cbranch_scc1 .LBB0_429
	v_add_u32_e32 v113, s40, v173
	v_add_u32_e32 v98, 32, v113
	v_cmp_le_i32_e32 vcc, v98, v172
	v_add_u32_e32 v100, 33, v113
	s_nop 0
	v_cndmask_b32_e32 v18, v227, v18, vcc
	v_cmp_lt_i32_e32 vcc, v113, v172
	s_nop 1
	v_cndmask_b32_e32 v99, v227, v35, vcc
	v_cmp_le_i32_e32 vcc, v113, v172
	v_add_u32_e32 v35, 34, v113
	s_nop 0
	v_cndmask_b32_e32 v98, v227, v34, vcc
	v_cmp_le_i32_e32 vcc, v100, v172
	v_add_u32_e32 v34, 2, v113
	s_nop 0
	v_cndmask_b32_e32 v19, v227, v19, vcc
	v_cmp_le_i32_e32 vcc, v34, v172
	v_add_u32_e32 v34, 3, v113
	s_nop 0
	v_cndmask_b32_e32 v100, v227, v36, vcc
	v_cmp_le_i32_e32 vcc, v35, v172
	v_add_u32_e32 v35, 35, v113
	s_nop 0
	v_cndmask_b32_e32 v20, v227, v20, vcc
	v_cmp_le_i32_e32 vcc, v34, v172
	v_add_u32_e32 v34, 8, v113
	s_nop 0
	v_cndmask_b32_e32 v101, v227, v37, vcc
	v_cmp_le_i32_e32 vcc, v35, v172
	v_add_u32_e32 v35, 40, v113
	s_nop 0
	v_cndmask_b32_e32 v21, v227, v21, vcc
	v_cmp_le_i32_e32 vcc, v34, v172
	v_add_u32_e32 v34, 9, v113
	s_nop 0
	v_cndmask_b32_e32 v102, v227, v38, vcc
	v_cmp_le_i32_e32 vcc, v35, v172
	v_add_u32_e32 v35, 41, v113
	s_nop 0
	v_cndmask_b32_e32 v22, v227, v22, vcc
	v_cmp_le_i32_e32 vcc, v34, v172
	v_add_u32_e32 v34, 10, v113
	s_nop 0
	v_cndmask_b32_e32 v103, v227, v39, vcc
	v_cmp_le_i32_e32 vcc, v35, v172
	v_add_u32_e32 v35, 42, v113
	s_nop 0
	v_cndmask_b32_e32 v23, v227, v23, vcc
	v_cmp_le_i32_e32 vcc, v34, v172
	v_add_u32_e32 v34, 11, v113
	s_nop 0
	v_cndmask_b32_e32 v104, v227, v40, vcc
	v_cmp_le_i32_e32 vcc, v35, v172
	v_add_u32_e32 v35, 43, v113
	s_nop 0
	v_cndmask_b32_e32 v24, v227, v24, vcc
	v_cmp_le_i32_e32 vcc, v34, v172
	v_add_u32_e32 v34, 16, v113
	s_nop 0
	v_cndmask_b32_e32 v105, v227, v41, vcc
	v_cmp_le_i32_e32 vcc, v35, v172
	v_add_u32_e32 v35, 48, v113
	s_nop 0
	v_cndmask_b32_e32 v25, v227, v25, vcc
	v_cmp_le_i32_e32 vcc, v34, v172
	v_add_u32_e32 v34, 17, v113
	s_nop 0
	v_cndmask_b32_e32 v106, v227, v42, vcc
	v_cmp_le_i32_e32 vcc, v35, v172
	v_add_u32_e32 v35, 49, v113
	s_nop 0
	v_cndmask_b32_e32 v26, v227, v26, vcc
	v_cmp_le_i32_e32 vcc, v34, v172
	v_add_u32_e32 v34, 18, v113
	s_nop 0
	v_cndmask_b32_e32 v107, v227, v43, vcc
	v_cmp_le_i32_e32 vcc, v35, v172
	v_add_u32_e32 v35, 50, v113
	s_nop 0
	v_cndmask_b32_e32 v27, v227, v27, vcc
	v_cmp_le_i32_e32 vcc, v34, v172
	v_add_u32_e32 v34, 19, v113
	s_nop 0
	v_cndmask_b32_e32 v108, v227, v44, vcc
	v_cmp_le_i32_e32 vcc, v35, v172
	v_add_u32_e32 v35, 51, v113
	s_nop 0
	v_cndmask_b32_e32 v28, v227, v28, vcc
	v_cmp_le_i32_e32 vcc, v34, v172
	v_add_u32_e32 v34, 24, v113
	s_nop 0
	v_cndmask_b32_e32 v109, v227, v45, vcc
	v_cmp_le_i32_e32 vcc, v35, v172
	v_add_u32_e32 v35, 56, v113
	s_nop 0
	v_cndmask_b32_e32 v29, v227, v29, vcc
	v_cmp_le_i32_e32 vcc, v34, v172
	v_add_u32_e32 v34, 25, v113
	s_nop 0
	v_cndmask_b32_e32 v110, v227, v46, vcc
	v_cmp_le_i32_e32 vcc, v35, v172
	v_add_u32_e32 v35, 57, v113
	s_nop 0
	v_cndmask_b32_e32 v30, v227, v30, vcc
	v_cmp_le_i32_e32 vcc, v34, v172
	v_add_u32_e32 v34, 26, v113
	s_nop 0
	v_cndmask_b32_e32 v111, v227, v47, vcc
	v_cmp_le_i32_e32 vcc, v35, v172
	v_add_u32_e32 v35, 58, v113
	s_nop 0
	v_cndmask_b32_e32 v31, v227, v31, vcc
	v_cmp_le_i32_e32 vcc, v34, v172
	v_add_u32_e32 v34, 27, v113
	s_nop 0
	v_cndmask_b32_e32 v112, v227, v48, vcc
	v_cmp_le_i32_e32 vcc, v35, v172
	v_add_u32_e32 v35, 59, v113
	s_nop 0
	v_cndmask_b32_e32 v32, v227, v32, vcc
	v_cmp_le_i32_e32 vcc, v34, v172
	s_nop 1
	v_cndmask_b32_e32 v113, v227, v49, vcc
	v_cmp_le_i32_e32 vcc, v35, v172
	s_nop 1
	v_cndmask_b32_e32 v33, v227, v33, vcc
	s_branch .LBB0_430

; #define LAS __attribute__((address_space(3)))
; #define MFMA32(a, b, c) __builtin_amdgcn_mfma_f32_32x32x16_bf16((a), (b), (c), 0, 0, 0)
; template <int DQ, int DK1, int DV, int MODE> ...
;     ...
;     auto qk = [&](int buf, f32x16& a0, f32x16& a1) {
; #pragma unroll
;         for (int i = 0; i < 16; ++i) { a0[i] = 0.f; a1[i] = 0.f; }
;         const LAS unsigned char* kb = lds + OFF_K + buf * KBYTES + r32 * KS + hi * 16;
; #pragma unroll
;         for (int ks = 0; ks < DQ / 16; ++ks) {
;             const bf16x8 k0 = *(const LAS bf16x8*)(kb + ks * 32), k1 = *(const LAS bf16x8*)(kb + 32 * KS + ks * 32);
;             a0 = MFMA32(k0, qf[ks], a0); a1 = MFMA32(k1, qf[ks], a1);
;         }
;     };
;     ...
;         bf16x8 pf[4];
;         {
;             qk(cur ^ 1, n0, n1);
;             float rs0 = 0.f, rs1 = 0.f;
; #pragma unroll
;             for (int i = 0; i < 16; ++i) { p0[i] = __builtin_amdgcn_exp2f(p0[i] - mn); p1[i] = __builtin_amdgcn_exp2f(p1[i] - mn); rs0 += p0[i]; rs1 += p1[i]; }
;             l_run += rs0 + rs1;
;             pf[0] = packp(p0, 0); pf[1] = packp(p0, 1); pf[2] = packp(p1, 0); pf[3] = packp(p1, 1);
;             __builtin_amdgcn_sched_group_barrier(0x100, 4, 0);
; #pragma unroll
;             for (int i = 0; i < DQ / 8; ++i) {
;                 __builtin_amdgcn_sched_group_barrier(0x100, 1, 0);
;                 __builtin_amdgcn_sched_group_barrier(0x008, 1, 0);
;                 __builtin_amdgcn_sched_group_barrier(0x002, DQ == 192 ? 4 : 12, 0);
;                 __builtin_amdgcn_sched_group_barrier(0x400, DQ == 192 ? 3 : 8, 0);
;             }
;             asm volatile("" : "+v"(pf[0]), "+v"(pf[1]), "+v"(pf[2]), "+v"(pf[3]), "+v"(l_run));
.LBB0_432:
	s_add_i32 s48, s28, -1
	s_cmp_ge_u32 s48, s29
	s_cbranch_scc1 .Lmla_qlite
	s_add_i32 s48, s86, -33
	s_cmp_gt_i32 s40, s48
	s_cbranch_scc1 .Lmla_qlite
	s_xor_b32 s48, s47, 1
	s_mulk_i32 s48, 0x6400
	v_sub_f32_e32 v34, v98, v205
	v_sub_f32_e32 v18, v18, v205
	v_sub_f32_e32 v35, v99, v205
	v_add_u32_e32 v206, s48, v1
	v_exp_f32_e32 v207, v34
	v_exp_f32_e32 v209, v18
	v_exp_f32_e32 v208, v35
	ds_read_b128 v[34:37], v206 offset:12800
	v_sub_f32_e32 v98, v19, v205
	v_sub_f32_e32 v99, v20, v205
	v_sub_f32_e32 v196, v21, v205
	v_sub_f32_e32 v197, v22, v205
	ds_read_b128 v[38:41], v206 offset:12832
	v_exp_f32_e32 v210, v98
	v_exp_f32_e32 v213, v99
	v_exp_f32_e32 v214, v196
	ds_read_b128 v[42:45], v206 offset:12864
	v_sub_f32_e32 v201, v26, v205
	v_sub_f32_e32 v198, v23, v205
	v_sub_f32_e32 v199, v24, v205
	v_sub_f32_e32 v200, v25, v205
	v_exp_f32_e32 v201, v201
	ds_read_b128 v[46:49], v206 offset:12896
	v_sub_f32_e32 v203, v27, v205
	v_sub_f32_e32 v215, v28, v205
	v_sub_f32_e32 v216, v29, v205
	v_sub_f32_e32 v217, v30, v205
	v_exp_f32_e32 v203, v203
	ds_read_b128 v[240:243], v206 offset:12928
	v_sub_f32_e32 v98, v100, v205
	v_sub_f32_e32 v220, v31, v205
	v_sub_f32_e32 v221, v32, v205
	v_sub_f32_e32 v232, v33, v205
	v_exp_f32_e32 v211, v98
	ds_read_b128 v[244:247], v206 offset:12960
	ds_read_b128 v[248:251], v206 offset:12992
	ds_read_b128 v[162:165], v206 offset:13024
	s_waitcnt lgkmcnt(7)
	v_mfma_f32_32x32x16_bf16 v[18:33], v[34:37], v[114:117], 0
	ds_read_b128 v[34:37], v206 offset:13056
	v_sub_f32_e32 v100, v101, v205
	v_exp_f32_e32 v212, v100
	s_mulk_i32 s47, 0x5000
	s_waitcnt lgkmcnt(7)
	v_mfma_f32_32x32x16_bf16 v[18:33], v[38:41], v[118:121], v[18:33]
	ds_read_b128 v[38:41], v206 offset:13088
	s_waitcnt lgkmcnt(7)
	v_mfma_f32_32x32x16_bf16 v[18:33], v[42:45], v[122:125], v[18:33]
	ds_read_b128 v[42:45], v206 offset:13120
	s_waitcnt lgkmcnt(7)
	v_mfma_f32_32x32x16_bf16 v[18:33], v[46:49], v[126:129], v[18:33]
	ds_read_b128 v[46:49], v206 offset:13152
	s_waitcnt lgkmcnt(7)
	v_mfma_f32_32x32x16_bf16 v[18:33], v[240:243], v[130:133], v[18:33]
	ds_read_b128 v[240:243], v206
	v_add_f32_e32 v166, 0, v209
	v_add_f32_e32 v166, v210, v166
	v_exp_f32_e32 v169, v198
	s_waitcnt lgkmcnt(7)
	v_mfma_f32_32x32x16_bf16 v[18:33], v[244:247], v[134:137], v[18:33]
	ds_read_b128 v[244:247], v206 offset:32
	v_exp_f32_e32 v193, v199
	v_exp_f32_e32 v199, v216
	s_waitcnt lgkmcnt(7)
	v_mfma_f32_32x32x16_bf16 v[18:33], v[248:251], v[138:141], v[18:33]
	ds_read_b128 v[248:251], v206 offset:64
	s_waitcnt lgkmcnt(7)
	v_mfma_f32_32x32x16_bf16 v[18:33], v[162:165], v[142:145], v[18:33]
	ds_read_b128 v[162:165], v206 offset:96
	s_waitcnt lgkmcnt(7)
	v_mfma_f32_32x32x16_bf16 v[18:33], v[34:37], v[146:149], v[18:33]
	s_waitcnt lgkmcnt(6)
	v_mfma_f32_32x32x16_bf16 v[18:33], v[38:41], v[150:153], v[18:33]
	s_waitcnt lgkmcnt(5)
	v_mfma_f32_32x32x16_bf16 v[18:33], v[42:45], v[154:157], v[18:33]
	s_waitcnt lgkmcnt(4)
	v_mfma_f32_32x32x16_bf16 v[18:33], v[46:49], v[158:161], v[18:33]
	v_add_f32_e32 v34, 0, v207
	v_add_f32_e32 v167, v208, v34
	s_waitcnt lgkmcnt(3)
	v_mfma_f32_32x32x16_bf16 v[34:49], v[240:243], v[114:117], 0
	ds_read_b128 v[240:243], v206 offset:128
	s_waitcnt lgkmcnt(3)
	v_mfma_f32_32x32x16_bf16 v[34:49], v[244:247], v[118:121], v[34:49]
	ds_read_b128 v[244:247], v206 offset:160
	v_add_f32_e32 v98, v211, v167
	v_add_f32_e32 v194, v212, v98
	v_sub_f32_e32 v98, v102, v205
	v_add_f32_e32 v99, v213, v166
	v_exp_f32_e32 v166, v98
	v_exp_f32_e32 v167, v197
	v_exp_f32_e32 v197, v215
	v_sub_f32_e32 v100, v103, v205
	v_sub_f32_e32 v102, v107, v205
	v_add_f32_e32 v195, v214, v99
	v_sub_f32_e32 v103, v111, v205
	v_exp_f32_e32 v168, v100
	v_exp_f32_e32 v107, v200
	v_exp_f32_e32 v202, v102
	s_waitcnt lgkmcnt(3)
	v_mfma_f32_32x32x16_bf16 v[34:49], v[248:251], v[122:125], v[34:49]
	ds_read_b128 v[248:251], v206 offset:192
	v_sub_f32_e32 v98, v104, v205
	v_sub_f32_e32 v99, v105, v205
	v_sub_f32_e32 v102, v110, v205
	v_sub_f32_e32 v110, v113, v205
	v_exp_f32_e32 v192, v98
	v_sub_f32_e32 v98, v106, v205
	v_exp_f32_e32 v106, v99
	v_exp_f32_e32 v200, v98
	s_waitcnt lgkmcnt(3)
	v_mfma_f32_32x32x16_bf16 v[34:49], v[162:165], v[126:129], v[34:49]
	ds_read_b128 v[162:165], v206 offset:224
	v_sub_f32_e32 v98, v108, v205
	v_sub_f32_e32 v99, v109, v205
	v_exp_f32_e32 v196, v98
	v_exp_f32_e32 v198, v99
	v_exp_f32_e32 v108, v102
	s_waitcnt lgkmcnt(3)
	v_mfma_f32_32x32x16_bf16 v[34:49], v[240:243], v[130:133], v[34:49]
	ds_read_b128 v[240:243], v206 offset:256
	v_add_f32_e64 v98, v166, v194
	v_add_f32_e64 v99, v167, v195
	v_sub_f32_e32 v100, v112, v205
	v_add_f32_e64 v98, v168, v98
	v_add_f32_e64 v99, v169, v99
	v_pk_add_f32 v[104:105], v[192:193], v[98:99]
	v_exp_f32_e32 v102, v100
	s_waitcnt lgkmcnt(3)
	v_mfma_f32_32x32x16_bf16 v[34:49], v[244:247], v[134:137], v[34:49]
	ds_read_b128 v[244:247], v206 offset:288
	v_add_f32_e64 v98, v106, v104
	v_add_f32_e64 v99, v107, v105
	v_add_f32_e64 v98, v200, v98
	v_add_f32_e64 v99, v201, v99
	v_add_f32_e64 v98, v202, v98
	v_add_f32_e64 v99, v203, v99
	v_pk_add_f32 v[98:99], v[196:197], v[98:99]
	s_nop 0
	v_pk_add_f32 v[98:99], v[198:199], v[98:99]
	v_exp_f32_e32 v109, v217
	s_nop 0
	v_pk_add_f32 v[98:99], v[108:109], v[98:99]
	v_exp_f32_e32 v194, v103
	v_exp_f32_e32 v195, v220
	v_cvt_pk_bf16_f32 v108, v108, v194
	v_pk_add_f32 v[98:99], v[194:195], v[98:99]
	v_exp_f32_e32 v103, v221
	v_exp_f32_e32 v104, v110
	v_pk_add_f32 v[110:111], v[102:103], v[98:99]
	s_waitcnt lgkmcnt(3)
	v_mfma_f32_32x32x16_bf16 v[34:49], v[248:251], v[138:141], v[34:49]
	ds_read_b128 v[248:251], v206 offset:320
	s_waitcnt lgkmcnt(3)
	v_mfma_f32_32x32x16_bf16 v[34:49], v[162:165], v[142:145], v[34:49]
	ds_read_b128 v[162:165], v206 offset:352
	s_waitcnt lgkmcnt(3)
	v_mfma_f32_32x32x16_bf16 v[34:49], v[240:243], v[146:149], v[34:49]
	s_waitcnt lgkmcnt(2)
	v_mfma_f32_32x32x16_bf16 v[34:49], v[244:247], v[150:153], v[34:49]
	v_cvt_pk_bf16_f32 v112, v166, v168
	v_cvt_pk_bf16_f32 v100, v109, v195
	v_cvt_pk_bf16_f32 v109, v102, v104
	v_exp_f32_e32 v105, v232
	s_nop 0
	v_pk_add_f32 v[110:111], v[104:105], v[110:111]
	v_cvt_pk_bf16_f32 v104, v167, v169
	s_waitcnt lgkmcnt(1)
	v_mfma_f32_32x32x16_bf16 v[34:49], v[248:251], v[154:157], v[34:49]
	v_add_u32_e32 v113, s47, v191
	v_cvt_pk_bf16_f32 v101, v103, v105
	v_cvt_pk_bf16_f32 v105, v193, v107
	v_add_u32_e32 v193, 0xc800, v113
	v_add_f32_e32 v107, v110, v111
	v_fmac_f32_e32 v107, v204, v190
	v_cvt_pk_bf16_f32 v110, v207, v208
	v_cvt_pk_bf16_f32 v111, v211, v212
	v_cvt_pk_bf16_f32 v102, v209, v210
	v_cvt_pk_bf16_f32 v103, v213, v214
	v_cvt_pk_bf16_f32 v98, v201, v203
	v_cvt_pk_bf16_f32 v99, v197, v199
	v_mov_b32_e32 v204, v107
	v_cvt_pk_bf16_f32 v113, v192, v106
	v_cvt_pk_bf16_f32 v106, v200, v202
	v_cvt_pk_bf16_f32 v107, v196, v198
	s_waitcnt lgkmcnt(0)
	v_mfma_f32_32x32x16_bf16 v[34:49], v[162:165], v[158:161], v[34:49]
; template <int DQ, int DK1, int DV, int MODE> ...
;     ...
;         {
;             const unsigned vba = (unsigned)(uintptr_t)(lds + OFF_V + cur * VBYTES + (4 * hi + ((lane & 15) >> 2)) * VS + (16 * ((lane >> 4) & 1) + 4 * (lane & 3)) * 2);
;             typedef short s16x4_t __attribute__((ext_vector_type(4)));
;             constexpr int DB = (DV / 32) >= 2 ? 2 : 1;
; #pragma unroll
;             for (int d0 = 0; d0 < DV / 32; d0 += DB) {
;                 s16x4_t lo[DB][4], hh[DB][4];
; #pragma unroll
;                 for (int dd = 0; dd < DB; ++dd)
; #pragma unroll
;                     for (int kk = 0; kk < 4; ++kk) {
;                         asm volatile("ds_read_b64_tr_b16 %0, %1 offset:%c2" : "=&v"(lo[dd][kk]) : "v"(vba), "i"((16 * kk) * VS + (d0 + dd) * 64) : "memory");
;                         asm volatile("ds_read_b64_tr_b16 %0, %1 offset:%c2" : "=&v"(hh[dd][kk]) : "v"(vba), "i"((16 * kk + 8) * VS + (d0 + dd) * 64) : "memory");
;                     }
;                 asm volatile("s_waitcnt lgkmcnt(0)" ::: "memory");
;                 __builtin_amdgcn_sched_barrier(0);
; #pragma unroll
;                 for (int dd = 0; dd < DB; ++dd)
; #pragma unroll
;                     for (int kk = 0; kk < 4; ++kk) {
;                         const bf16x8 vf = {lo[dd][kk][0], lo[dd][kk][1], lo[dd][kk][2], lo[dd][kk][3], hh[dd][kk][0], hh[dd][kk][1], hh[dd][kk][2], hh[dd][kk][3]};
;                         o[d0 + dd] = MFMA32(vf, pf[kk], o[d0 + dd]);
;                     }
;             }
;         }
;         if (more1) store_ck(cur ^ 1);
;         asm volatile("s_waitcnt vmcnt(0)" ::: "memory");
;         __syncthreads();
;         p0 = n0; p1 = n1;
;     }
;     float l; { auto rr = __builtin_amdgcn_permlane32_swap(__float_as_uint(l_run), __float_as_uint(l_run), false, false); l = __uint_as_float(rr[0]) + __uint_as_float(rr[1]); }
;     if (MODE == 2) l += __builtin_amdgcn_exp2f(sink2 - m_run);
;     const float inv = 1.0f / l;
;     bf16_t* orow = Op + (tok0 + qpos) * (size_t)DM;
; #pragma unroll
;     for (int d = 0; d < DV / 32; ++d)
; #pragma unroll
;         for (int g = 0; g < 4; ++g) { u32x2 w; w[0] = pk2(o[d][4 * g] * inv, o[d][4 * g + 1] * inv); w[1] = pk2(o[d][4 * g + 2] * inv, o[d][4 * g + 3] * inv);
;             *(u32x2*)(orow + 32 * d + 8 * g + 4 * hi) = w; }
.Lmla_qjoin:
	ds_read_b64_tr_b16 v[166:167], v193 offset:0
	ds_read_b64_tr_b16 v[168:169], v193 offset:2560
	ds_read_b64_tr_b16 v[194:195], v193 offset:5120
	ds_read_b64_tr_b16 v[196:197], v193 offset:7680
	ds_read_b64_tr_b16 v[198:199], v193 offset:10240
	ds_read_b64_tr_b16 v[200:201], v193 offset:12800
	ds_read_b64_tr_b16 v[206:207], v193 offset:15360
	ds_read_b64_tr_b16 v[208:209], v193 offset:17920
	ds_read_b64_tr_b16 v[210:211], v193 offset:64
	ds_read_b64_tr_b16 v[212:213], v193 offset:2624
	ds_read_b64_tr_b16 v[214:215], v193 offset:5184
	ds_read_b64_tr_b16 v[216:217], v193 offset:7744
	ds_read_b64_tr_b16 v[232:233], v193 offset:10304
	ds_read_b64_tr_b16 v[234:235], v193 offset:12864
	ds_read_b64_tr_b16 v[236:237], v193 offset:15424
	ds_read_b64_tr_b16 v[238:239], v193 offset:17984
	s_waitcnt lgkmcnt(0)
	s_nop 0
	v_mfma_f32_32x32x16_bf16 v[82:97], v[166:169], v[110:113], v[82:97]
	ds_read_b64_tr_b16 v[166:167], v193 offset:128
	ds_read_b64_tr_b16 v[168:169], v193 offset:2688
	v_mfma_f32_32x32x16_bf16 v[66:81], v[210:213], v[110:113], v[66:81]
	v_mfma_f32_32x32x16_bf16 v[82:97], v[194:197], v[106:109], v[82:97]
	ds_read_b64_tr_b16 v[194:195], v193 offset:5248
	ds_read_b64_tr_b16 v[196:197], v193 offset:7808
	v_mfma_f32_32x32x16_bf16 v[66:81], v[214:217], v[106:109], v[66:81]
	v_mfma_f32_32x32x16_bf16 v[82:97], v[198:201], v[102:105], v[82:97]
	ds_read_b64_tr_b16 v[198:199], v193 offset:10368
	ds_read_b64_tr_b16 v[200:201], v193 offset:12928
	v_mfma_f32_32x32x16_bf16 v[66:81], v[232:235], v[102:105], v[66:81]
	v_mfma_f32_32x32x16_bf16 v[82:97], v[206:209], v[98:101], v[82:97]
	ds_read_b64_tr_b16 v[206:207], v193 offset:15488
	ds_read_b64_tr_b16 v[208:209], v193 offset:18048
	ds_read_b64_tr_b16 v[210:211], v193 offset:192
	ds_read_b64_tr_b16 v[212:213], v193 offset:2752
	ds_read_b64_tr_b16 v[214:215], v193 offset:5312
	ds_read_b64_tr_b16 v[216:217], v193 offset:7872
	ds_read_b64_tr_b16 v[232:233], v193 offset:10432
	v_mfma_f32_32x32x16_bf16 v[66:81], v[236:239], v[98:101], v[66:81]
	ds_read_b64_tr_b16 v[234:235], v193 offset:12992
	ds_read_b64_tr_b16 v[236:237], v193 offset:15552
	ds_read_b64_tr_b16 v[238:239], v193 offset:18112
	s_waitcnt lgkmcnt(0)
	v_mfma_f32_32x32x16_bf16 v[50:65], v[166:169], v[110:113], v[50:65]
	s_add_i32 s40, s40, 64
	s_add_u32 s35, s35, 0x2000
	s_addc_u32 s36, s36, 0
	s_waitcnt vmcnt(0)
	s_add_u32 s44, s44, 0x20000
	s_addc_u32 s45, s45, 0
	s_add_i32 s28, s28, 1
	v_mfma_f32_32x32x16_bf16 v[2:17], v[210:213], v[110:113], v[2:17]
	v_lshl_add_u64 v[184:185], v[184:185], 0, s[82:83]
	v_lshl_add_u64 v[186:187], v[186:187], 0, s[82:83]
	v_lshl_add_u64 v[188:189], v[188:189], 0, s[82:83]
	s_cmp_lg_u32 s46, s40
	s_waitcnt vmcnt(0)
	s_barrier
	v_mfma_f32_32x32x16_bf16 v[50:65], v[194:197], v[106:109], v[50:65]
	v_mfma_f32_32x32x16_bf16 v[2:17], v[214:217], v[106:109], v[2:17]
	v_mfma_f32_32x32x16_bf16 v[50:65], v[198:201], v[102:105], v[50:65]
	v_mfma_f32_32x32x16_bf16 v[2:17], v[232:235], v[102:105], v[2:17]
	v_mfma_f32_32x32x16_bf16 v[50:65], v[206:209], v[98:101], v[50:65]
	v_mfma_f32_32x32x16_bf16 v[2:17], v[236:239], v[98:101], v[2:17]
	s_cbranch_scc1 .LBB0_411
.Lmla_epi:
	v_mov_b32_e32 v1, v204
	s_nop 1
	v_permlane32_swap_b32_e32 v204, v1
	v_add_f32_e32 v1, v204, v1
	s_nop 5
	v_div_scale_f32 v18, s[2:3], v1, v1, 1.0
	v_rcp_f32_e32 v19, v18
	v_readlane_b32 s2, v255, 1
	s_add_u32 s2, s2, s87
	s_addc_u32 s3, s34, 0
	v_fma_f32 v20, -v18, v19, 1.0
	v_fmac_f32_e32 v19, v20, v19
	v_div_scale_f32 v20, vcc, 1.0, v1, 1.0
	v_mul_f32_e32 v21, v20, v19
	v_fma_f32 v22, -v18, v21, v20
	v_fmac_f32_e32 v21, v22, v19
	v_fma_f32 v18, -v18, v21, v20
	v_div_fmas_f32 v18, v18, v19, v21
	v_lshlrev_b64 v[20:21], 12, v[170:171]
	v_div_fixup_f32 v18, v18, v1, 1.0
	v_lshl_add_u64 v[20:21], s[2:3], 0, v[20:21]
	v_lshlrev_b32_e32 v22, 1, v173
	v_mov_b32_e32 v23, v0
	v_lshl_add_u64 v[20:21], v[20:21], 0, v[22:23]
	v_pk_mul_f32 v[22:23], v[82:83], v[18:19] op_sel_hi:[1,0]
	v_pk_mul_f32 v[24:25], v[84:85], v[18:19] op_sel_hi:[1,0]
	v_cvt_pk_bf16_f32 v22, v22, v23
	v_cvt_pk_bf16_f32 v23, v24, v25
	global_store_dwordx2 v[20:21], v[22:23], off
	v_pk_mul_f32 v[22:23], v[86:87], v[18:19] op_sel_hi:[1,0]
	v_pk_mul_f32 v[24:25], v[88:89], v[18:19] op_sel_hi:[1,0]
	v_cvt_pk_bf16_f32 v22, v22, v23
	v_cvt_pk_bf16_f32 v23, v24, v25
	global_store_dwordx2 v[20:21], v[22:23], off offset:16
	v_pk_mul_f32 v[22:23], v[90:91], v[18:19] op_sel_hi:[1,0]
	v_pk_mul_f32 v[24:25], v[92:93], v[18:19] op_sel_hi:[1,0]
	v_cvt_pk_bf16_f32 v22, v22, v23
	v_cvt_pk_bf16_f32 v23, v24, v25
	global_store_dwordx2 v[20:21], v[22:23], off offset:32
	v_pk_mul_f32 v[22:23], v[94:95], v[18:19] op_sel_hi:[1,0]
	v_pk_mul_f32 v[24:25], v[96:97], v[18:19] op_sel_hi:[1,0]
	v_cvt_pk_bf16_f32 v22, v22, v23
	v_cvt_pk_bf16_f32 v23, v24, v25
	global_store_dwordx2 v[20:21], v[22:23], off offset:48
	v_pk_mul_f32 v[22:23], v[66:67], v[18:19] op_sel_hi:[1,0]
	v_pk_mul_f32 v[24:25], v[68:69], v[18:19] op_sel_hi:[1,0]
	v_cvt_pk_bf16_f32 v22, v22, v23
	v_cvt_pk_bf16_f32 v23, v24, v25
	global_store_dwordx2 v[20:21], v[22:23], off offset:64
	v_pk_mul_f32 v[22:23], v[70:71], v[18:19] op_sel_hi:[1,0]
	v_pk_mul_f32 v[24:25], v[72:73], v[18:19] op_sel_hi:[1,0]
	v_cvt_pk_bf16_f32 v22, v22, v23
	v_cvt_pk_bf16_f32 v23, v24, v25
	global_store_dwordx2 v[20:21], v[22:23], off offset:80
	v_pk_mul_f32 v[22:23], v[74:75], v[18:19] op_sel_hi:[1,0]
	v_pk_mul_f32 v[24:25], v[76:77], v[18:19] op_sel_hi:[1,0]
	v_cvt_pk_bf16_f32 v22, v22, v23
	v_cvt_pk_bf16_f32 v23, v24, v25
	global_store_dwordx2 v[20:21], v[22:23], off offset:96
	v_pk_mul_f32 v[22:23], v[78:79], v[18:19] op_sel_hi:[1,0]
	v_pk_mul_f32 v[24:25], v[80:81], v[18:19] op_sel_hi:[1,0]
; __device__ __forceinline__ unsigned pk2(float lo, float hi) { f32x2 v = {lo, hi}; bf16x2_t b = __builtin_convertvector(v, bf16x2_t); return __builtin_bit_cast(unsigned, b); }
; template <int DQ, int DK1, int DV, int MODE> ...
;     ...
;         bf16x8 pf[4];
;         {
;             qk(cur ^ 1, n0, n1);
;             float rs0 = 0.f, rs1 = 0.f;
; #pragma unroll
;             for (int i = 0; i < 16; ++i) { p0[i] = __builtin_amdgcn_exp2f(p0[i] - mn); p1[i] = __builtin_amdgcn_exp2f(p1[i] - mn); rs0 += p0[i]; rs1 += p1[i]; }
;             l_run += rs0 + rs1;
;             pf[0] = packp(p0, 0); pf[1] = packp(p0, 1); pf[2] = packp(p1, 0); pf[3] = packp(p1, 1);
;             __builtin_amdgcn_sched_group_barrier(0x100, 4, 0);
; #pragma unroll
;             for (int i = 0; i < DQ / 8; ++i) {
;                 __builtin_amdgcn_sched_group_barrier(0x100, 1, 0);
;                 __builtin_amdgcn_sched_group_barrier(0x008, 1, 0);
;                 __builtin_amdgcn_sched_group_barrier(0x002, DQ == 192 ? 4 : 12, 0);
;                 __builtin_amdgcn_sched_group_barrier(0x400, DQ == 192 ? 3 : 8, 0);
;             }
;             asm volatile("" : "+v"(pf[0]), "+v"(pf[1]), "+v"(pf[2]), "+v"(pf[3]), "+v"(l_run));
;     ...
;     float l; { auto rr = __builtin_amdgcn_permlane32_swap(__float_as_uint(l_run), __float_as_uint(l_run), false, false); l = __uint_as_float(rr[0]) + __uint_as_float(rr[1]); }
;     if (MODE == 2) l += __builtin_amdgcn_exp2f(sink2 - m_run);
;     const float inv = 1.0f / l;
;     bf16_t* orow = Op + (tok0 + qpos) * (size_t)DM;
; #pragma unroll
;     for (int d = 0; d < DV / 32; ++d)
; #pragma unroll
;         for (int g = 0; g < 4; ++g) { u32x2 w; w[0] = pk2(o[d][4 * g] * inv, o[d][4 * g + 1] * inv); w[1] = pk2(o[d][4 * g + 2] * inv, o[d][4 * g + 3] * inv);
;             *(u32x2*)(orow + 32 * d + 8 * g + 4 * hi) = w; }
	v_cvt_pk_bf16_f32 v22, v22, v23
	v_cvt_pk_bf16_f32 v23, v24, v25
	global_store_dwordx2 v[20:21], v[22:23], off offset:112
	v_pk_mul_f32 v[22:23], v[50:51], v[18:19] op_sel_hi:[1,0]
	v_pk_mul_f32 v[24:25], v[52:53], v[18:19] op_sel_hi:[1,0]
	v_pk_mul_f32 v[2:3], v[2:3], v[18:19] op_sel_hi:[1,0]
	v_pk_mul_f32 v[4:5], v[4:5], v[18:19] op_sel_hi:[1,0]
	v_cvt_pk_bf16_f32 v22, v22, v23
	v_cvt_pk_bf16_f32 v23, v24, v25
	v_cvt_pk_bf16_f32 v2, v2, v3
	v_cvt_pk_bf16_f32 v3, v4, v5
	global_store_dwordx2 v[20:21], v[22:23], off offset:128
	v_pk_mul_f32 v[22:23], v[54:55], v[18:19] op_sel_hi:[1,0]
	v_pk_mul_f32 v[24:25], v[56:57], v[18:19] op_sel_hi:[1,0]
	global_store_dwordx2 v[20:21], v[2:3], off offset:192
	v_pk_mul_f32 v[2:3], v[6:7], v[18:19] op_sel_hi:[1,0]
	v_pk_mul_f32 v[4:5], v[8:9], v[18:19] op_sel_hi:[1,0]
	v_cvt_pk_bf16_f32 v22, v22, v23
	v_cvt_pk_bf16_f32 v23, v24, v25
	v_cvt_pk_bf16_f32 v2, v2, v3
	v_cvt_pk_bf16_f32 v3, v4, v5
	global_store_dwordx2 v[20:21], v[22:23], off offset:144
	v_pk_mul_f32 v[22:23], v[58:59], v[18:19] op_sel_hi:[1,0]
	v_pk_mul_f32 v[24:25], v[60:61], v[18:19] op_sel_hi:[1,0]
	global_store_dwordx2 v[20:21], v[2:3], off offset:208
	v_pk_mul_f32 v[2:3], v[10:11], v[18:19] op_sel_hi:[1,0]
	v_pk_mul_f32 v[4:5], v[12:13], v[18:19] op_sel_hi:[1,0]
	v_cvt_pk_bf16_f32 v22, v22, v23
	v_cvt_pk_bf16_f32 v23, v24, v25
	v_cvt_pk_bf16_f32 v2, v2, v3
	v_cvt_pk_bf16_f32 v3, v4, v5
	v_readlane_b32 s86, v254, 23
	global_store_dwordx2 v[20:21], v[22:23], off offset:160
	v_pk_mul_f32 v[22:23], v[62:63], v[18:19] op_sel_hi:[1,0]
	v_pk_mul_f32 v[24:25], v[64:65], v[18:19] op_sel_hi:[1,0]
	global_store_dwordx2 v[20:21], v[2:3], off offset:224
	v_pk_mul_f32 v[2:3], v[14:15], v[18:19] op_sel_hi:[1,0]
	v_pk_mul_f32 v[4:5], v[16:17], v[18:19] op_sel_hi:[1,0]
	v_readlane_b32 s87, v254, 24
	v_cvt_pk_bf16_f32 v22, v22, v23
	v_cvt_pk_bf16_f32 v23, v24, v25
	v_cvt_pk_bf16_f32 v2, v2, v3
	v_cvt_pk_bf16_f32 v3, v4, v5
	s_movk_i32 s89, 0x4000
	s_mov_b32 s87, 0x5980000
	s_mov_b64 s[90:91], 0x17800000
	global_store_dwordx2 v[20:21], v[22:23], off offset:176
	global_store_dwordx2 v[20:21], v[2:3], off offset:240
	s_setprio 0
	s_branch .LBB0_92
.Lmla_drone:
	s_add_i32 s40, s40, 64
	s_add_u32 s35, s35, 0x2000
	s_addc_u32 s36, s36, 0
	s_add_u32 s44, s44, 0x20000
	s_addc_u32 s45, s45, 0
	s_add_i32 s28, s28, 1
	v_lshl_add_u64 v[184:185], v[184:185], 0, s[82:83]
	v_lshl_add_u64 v[186:187], v[186:187], 0, s[82:83]
	v_lshl_add_u64 v[188:189], v[188:189], 0, s[82:83]
	s_waitcnt vmcnt(0)
	s_barrier
	s_cmp_lg_u32 s46, s40
	s_cbranch_scc1 .LBB0_411
	s_branch .Lmla_epi
.Lmla_qlite:
	s_xor_b32 s48, s47, 1
	s_mulk_i32 s48, 0x6400
	v_sub_f32_e32 v34, v98, v205
	v_sub_f32_e32 v18, v18, v205
	v_sub_f32_e32 v35, v99, v205
	v_add_u32_e32 v206, s48, v1
	v_exp_f32_e32 v207, v34
	v_exp_f32_e32 v209, v18
	v_exp_f32_e32 v208, v35
	v_sub_f32_e32 v98, v19, v205
	v_sub_f32_e32 v99, v20, v205
	v_sub_f32_e32 v196, v21, v205
	v_sub_f32_e32 v197, v22, v205
	v_exp_f32_e32 v210, v98
	v_exp_f32_e32 v213, v99
	v_exp_f32_e32 v214, v196
	v_sub_f32_e32 v201, v26, v205
	v_sub_f32_e32 v198, v23, v205
	v_sub_f32_e32 v199, v24, v205
	v_sub_f32_e32 v200, v25, v205
	v_exp_f32_e32 v201, v201
	v_sub_f32_e32 v203, v27, v205
	v_sub_f32_e32 v215, v28, v205
	v_sub_f32_e32 v216, v29, v205
	v_sub_f32_e32 v217, v30, v205
	v_exp_f32_e32 v203, v203
	v_sub_f32_e32 v98, v100, v205
	v_sub_f32_e32 v220, v31, v205
	v_sub_f32_e32 v221, v32, v205
	v_sub_f32_e32 v232, v33, v205
	v_exp_f32_e32 v211, v98
	v_sub_f32_e32 v100, v101, v205
	v_exp_f32_e32 v212, v100
	s_mulk_i32 s47, 0x5000
	v_add_f32_e32 v166, 0, v209
	v_add_f32_e32 v166, v210, v166
	v_exp_f32_e32 v169, v198
	v_exp_f32_e32 v193, v199
	v_exp_f32_e32 v199, v216
	v_add_f32_e32 v34, 0, v207
	v_add_f32_e32 v167, v208, v34
	v_add_f32_e32 v98, v211, v167
	v_add_f32_e32 v194, v212, v98
	v_sub_f32_e32 v98, v102, v205
	v_add_f32_e32 v99, v213, v166
	v_exp_f32_e32 v166, v98
	v_exp_f32_e32 v167, v197
	v_exp_f32_e32 v197, v215
	v_sub_f32_e32 v100, v103, v205
	v_sub_f32_e32 v102, v107, v205
	v_add_f32_e32 v195, v214, v99
	v_sub_f32_e32 v103, v111, v205
	v_exp_f32_e32 v168, v100
	v_exp_f32_e32 v107, v200
	v_exp_f32_e32 v202, v102
	v_sub_f32_e32 v98, v104, v205
	v_sub_f32_e32 v99, v105, v205
	v_sub_f32_e32 v102, v110, v205
	v_sub_f32_e32 v110, v113, v205
	v_exp_f32_e32 v192, v98
	v_sub_f32_e32 v98, v106, v205
	v_exp_f32_e32 v106, v99
	v_exp_f32_e32 v200, v98
	v_sub_f32_e32 v98, v108, v205
	v_sub_f32_e32 v99, v109, v205
	v_exp_f32_e32 v196, v98
	v_exp_f32_e32 v198, v99
	v_exp_f32_e32 v108, v102
	v_add_f32_e64 v98, v166, v194
	v_add_f32_e64 v99, v167, v195
	v_sub_f32_e32 v100, v112, v205
	v_add_f32_e64 v98, v168, v98
	v_add_f32_e64 v99, v169, v99
	v_pk_add_f32 v[104:105], v[192:193], v[98:99]
	v_exp_f32_e32 v102, v100
	v_add_f32_e64 v98, v106, v104
	v_add_f32_e64 v99, v107, v105
	v_add_f32_e64 v98, v200, v98
	v_add_f32_e64 v99, v201, v99
	v_add_f32_e64 v98, v202, v98
	v_add_f32_e64 v99, v203, v99
	v_pk_add_f32 v[98:99], v[196:197], v[98:99]
	s_nop 0
	v_pk_add_f32 v[98:99], v[198:199], v[98:99]
	v_exp_f32_e32 v109, v217
	s_nop 0
	v_pk_add_f32 v[98:99], v[108:109], v[98:99]
	v_exp_f32_e32 v194, v103
	v_exp_f32_e32 v195, v220
	v_cvt_pk_bf16_f32 v108, v108, v194
	v_pk_add_f32 v[98:99], v[194:195], v[98:99]
	v_exp_f32_e32 v103, v221
	v_exp_f32_e32 v104, v110
	v_pk_add_f32 v[110:111], v[102:103], v[98:99]
	v_cvt_pk_bf16_f32 v112, v166, v168
	v_cvt_pk_bf16_f32 v100, v109, v195
	v_cvt_pk_bf16_f32 v109, v102, v104
	v_exp_f32_e32 v105, v232
	s_nop 0
	v_pk_add_f32 v[110:111], v[104:105], v[110:111]
	v_cvt_pk_bf16_f32 v104, v167, v169
	v_add_u32_e32 v113, s47, v191
	v_cvt_pk_bf16_f32 v101, v103, v105
	v_cvt_pk_bf16_f32 v105, v193, v107
	v_add_u32_e32 v193, 0xc800, v113
	v_add_f32_e32 v107, v110, v111
	v_fmac_f32_e32 v107, v204, v190
	v_cvt_pk_bf16_f32 v110, v207, v208
	v_cvt_pk_bf16_f32 v111, v211, v212
	v_cvt_pk_bf16_f32 v102, v209, v210
	v_cvt_pk_bf16_f32 v103, v213, v214
	v_cvt_pk_bf16_f32 v98, v201, v203
	v_cvt_pk_bf16_f32 v99, v197, v199
	v_mov_b32_e32 v204, v107
	v_cvt_pk_bf16_f32 v113, v192, v106
	v_cvt_pk_bf16_f32 v106, v200, v202
	v_cvt_pk_bf16_f32 v107, v196, v198
	s_branch .Lmla_qjoin

; __device__ __forceinline__ unsigned pk2(float lo, float hi) { f32x2 v = {lo, hi}; bf16x2_t b = __builtin_convertvector(v, bf16x2_t); return __builtin_bit_cast(unsigned, b); }
; __device__ __forceinline__ f32x4 bf_lo4(const u32x4& w) { return (f32x4){__uint_as_float(w[0] << 16), __uint_as_float(w[0] & 0xffff0000u), __uint_as_float(w[1] << 16), __uint_as_float(w[1] & 0xffff0000u)}; }
; __device__ __forceinline__ f32x4 bf_hi4(const u32x4& w) { return (f32x4){__uint_as_float(w[2] << 16), __uint_as_float(w[2] & 0xffff0000u), __uint_as_float(w[3] << 16), __uint_as_float(w[3] & 0xffff0000u)}; }
; __device__ __forceinline__ void epi_resid(bf16_t* XB, float* SS, float alpha, const f32x4 (&acc)[2][2][4][2], const Unit& u, int wr, int wc, int fr, int fq) {
;     const int c0 = u.pn * 256 + wc * 32 + fq * 8;
;     u32x4 pre[2][2];
;     { const bf16_t* p = XB + (size_t)opaque(EPI_ROW(0)) * DM + c0; pre[0][0] = *(const u32x4*)p; pre[0][1] = *(const u32x4*)(p + 128); }
; #pragma unroll
;     for (int it = 0; it < 8; ++it) {
;         const int ai = it >> 2, m = it & 3; const int r = opaque(EPI_ROW(it));
;         if (it + 1 < 8) { const bf16_t* p = XB + (size_t)opaque(EPI_ROW(it + 1)) * DM + c0; pre[(it + 1) & 1][0] = *(const u32x4*)p; pre[(it + 1) & 1][1] = *(const u32x4*)(p + 128); }
;         float q = 0.f;
; #pragma unroll
;         for (int bj = 0; bj < 2; ++bj) {
;             const size_t off = (size_t)r * DM + c0 + bj * 128;
;             const u32x4 bw = pre[it & 1][bj];
;             const f32x4 o0 = bf_lo4(bw) + acc[ai][bj][m][0] * alpha, o1 = bf_hi4(bw) + acc[ai][bj][m][1] * alpha;
;             u32x4 w; w[0] = pk2(o0[0], o0[1]); w[1] = pk2(o0[2], o0[3]); w[2] = pk2(o1[0], o1[1]); w[3] = pk2(o1[2], o1[3]);
;             *(u32x4*)(XB + off) = w;
;             q += (o0[0] * o0[0] + o0[1] * o0[1]) + (o0[2] * o0[2] + o0[3] * o0[3]) + (o1[0] * o1[0] + o1[1] * o1[1]) + (o1[2] * o1[2] + o1[3] * o1[3]);
;         }
;         q += __shfl_xor(q, 16); q += __shfl_xor(q, 32);
;         if (fq == 0) SS[(size_t)r * 32 + u.pn * 4 + wc] = q;
;         asm volatile("" ::: "memory");
;     }
; }
.LBB0_733:
	s_andn2_b64 vcc, exec, s[2:3]
	s_cbranch_vccnz .LBB0_754
	s_cmp_gt_i32 s88, 0
	s_mov_b64 s[2:3], -1
	s_cbranch_scc0 .LBB0_752
	s_mov_b64 s[2:3], s[96:97]
	s_add_u32 s12, s2, 0x13800000
	s_addc_u32 s13, s3, 0
	s_add_u32 s2, s2, 0x17800000
	s_addc_u32 s3, s3, 0
	s_lshl_b32 s14, s81, 8
	v_add_u32_e32 v138, s14, v193
	v_mov_b32_e32 v132, v138
	v_lshl_or_b32 v130, s77, 8, v194
	s_waitcnt lgkmcnt(0)
	v_ashrrev_i32_e32 v131, 31, v130
	v_ashrrev_i32_e32 v133, 31, v132
	v_lshlrev_b64 v[132:133], 12, v[132:133]
	v_lshl_add_u64 v[132:133], s[12:13], 0, v[132:133]
	v_lshlrev_b64 v[130:131], 1, v[130:131]
	v_lshl_add_u64 v[132:133], v[132:133], 0, v[130:131]
	global_load_dwordx4 v[140:143], v[132:133], off
	global_load_dwordx4 v[152:155], v[132:133], off offset:256
	v_add_u32_e32 v146, s14, v233
	v_lshl_add_u64 v[150:151], s[12:13], 0, v[130:131]
	v_mov_b32_e32 v130, v146
	s_waitcnt vmcnt(0) lgkmcnt(0)
	v_lshlrev_b32_e32 v148, 16, v140
	v_ashrrev_i32_e32 v131, 31, v130
	v_lshlrev_b64 v[130:131], 12, v[130:131]
	v_lshl_add_u64 v[130:131], v[150:151], 0, v[130:131]
	global_load_dwordx4 v[134:137], v[130:131], off
	s_nop 0
	global_load_dwordx4 v[130:133], v[130:131], off offset:256
	v_and_b32_e32 v149, 0xffff0000, v140
	v_lshlrev_b32_e32 v140, 16, v141
	v_and_b32_e32 v141, 0xffff0000, v141
	v_ashrrev_i32_e32 v139, 31, v138
	v_pk_fma_f32 v[156:157], v[128:129], s[46:47], v[140:141]
	v_lshlrev_b32_e32 v140, 16, v142
	v_and_b32_e32 v141, 0xffff0000, v142
	v_lshlrev_b32_e32 v142, 16, v143
	v_and_b32_e32 v143, 0xffff0000, v143
	v_lshlrev_b64 v[144:145], 12, v[138:139]
	v_pk_fma_f32 v[148:149], v[126:127], s[40:41], v[148:149]
	v_pk_fma_f32 v[158:159], v[120:121], s[46:47], v[142:143]
	v_pk_fma_f32 v[160:161], v[118:119], s[40:41], v[140:141]
	v_lshl_add_u64 v[144:145], v[150:151], 0, v[144:145]
	v_cvt_pk_bf16_f32 v140, v148, v149
	v_cvt_pk_bf16_f32 v141, v156, v157
	v_cvt_pk_bf16_f32 v142, v160, v161
	v_cvt_pk_bf16_f32 v143, v158, v159
	global_store_dwordx4 v[144:145], v[140:143], off
	s_nop 1
	v_mul_f32_e32 v140, v149, v149
	v_mul_f32_e32 v141, v157, v157
	v_fmac_f32_e32 v140, v148, v148
	v_fmac_f32_e32 v141, v156, v156
	v_add_f32_e32 v140, v140, v141
	v_mul_f32_e32 v141, v161, v161
	v_fmac_f32_e32 v141, v160, v160
	v_add_f32_e32 v140, v141, v140
	v_mul_f32_e32 v141, v159, v159
	v_fmac_f32_e32 v141, v158, v158
	v_add_f32_e32 v147, v141, v140
	v_lshlrev_b32_e32 v140, 16, v152
	v_and_b32_e32 v141, 0xffff0000, v152
	v_lshlrev_b32_e32 v142, 16, v153
	v_and_b32_e32 v143, 0xffff0000, v153
	v_pk_fma_f32 v[148:149], v[124:125], s[46:47], v[142:143]
	v_pk_fma_f32 v[152:153], v[122:123], s[40:41], v[140:141]
	v_lshlrev_b32_e32 v140, 16, v154
	v_and_b32_e32 v141, 0xffff0000, v154
	v_lshlrev_b32_e32 v142, 16, v155
	v_and_b32_e32 v143, 0xffff0000, v155
	v_pk_fma_f32 v[154:155], v[116:117], s[46:47], v[142:143]
	v_pk_fma_f32 v[156:157], v[114:115], s[40:41], v[140:141]
	v_cvt_pk_bf16_f32 v140, v152, v153
	v_cvt_pk_bf16_f32 v141, v148, v149
	v_cvt_pk_bf16_f32 v142, v156, v157
	v_cvt_pk_bf16_f32 v143, v154, v155
	global_store_dwordx4 v[144:145], v[140:143], off offset:256
	s_nop 1
	v_mul_f32_e32 v140, v153, v153
	v_mul_f32_e32 v141, v149, v149
	v_fmac_f32_e32 v140, v152, v152
	v_fmac_f32_e32 v141, v148, v148
	v_add_f32_e32 v140, v140, v141
	v_mul_f32_e32 v141, v157, v157
	v_fmac_f32_e32 v141, v156, v156
	v_add_f32_e32 v140, v141, v140
	v_mul_f32_e32 v141, v155, v155
	v_fmac_f32_e32 v141, v154, v154
	v_and_b32_e32 v142, 64, v228
	v_add_f32_e32 v140, v141, v140
	v_xor_b32_e32 v141, 16, v228
	v_add_u32_e32 v142, 64, v142
	v_cmp_lt_i32_e32 vcc, v141, v142
	v_add_f32_e32 v140, v147, v140
	s_nop 0
	v_cndmask_b32_e32 v141, v228, v141, vcc
	v_lshlrev_b32_e32 v156, 2, v141
	ds_bpermute_b32 v141, v156, v140
	s_waitcnt lgkmcnt(0)
	v_add_f32_e32 v140, v140, v141
	v_xor_b32_e32 v141, 32, v228
	v_cmp_lt_i32_e32 vcc, v141, v142
	s_nop 1
	v_cndmask_b32_e32 v141, v228, v141, vcc
	v_lshlrev_b32_e32 v157, 2, v141
	ds_bpermute_b32 v141, v157, v140
	s_and_saveexec_b64 s[12:13], s[8:9]
	v_readlane_b32 s18, v254, 30
	s_cbranch_execz .LBB0_737
	s_lshl_b32 s16, s77, 2
	v_lshlrev_b64 v[138:139], 7, v[138:139]
	s_ashr_i32 s17, s16, 31
	v_lshl_add_u64 v[138:139], s[2:3], 0, v[138:139]
	v_lshl_add_u64 v[138:139], s[16:17], 2, v[138:139]
	s_lshl_b32 s36, s18, 2
	s_waitcnt lgkmcnt(0)
	v_add_f32_e32 v140, v140, v141
	v_lshl_add_u64 v[138:139], v[138:139], 0, s[36:37]
	global_store_dword v[138:139], v140, off
; __device__ __forceinline__ unsigned pk2(float lo, float hi) { f32x2 v = {lo, hi}; bf16x2_t b = __builtin_convertvector(v, bf16x2_t); return __builtin_bit_cast(unsigned, b); }
; __device__ __forceinline__ f32x4 bf_lo4(const u32x4& w) { return (f32x4){__uint_as_float(w[0] << 16), __uint_as_float(w[0] & 0xffff0000u), __uint_as_float(w[1] << 16), __uint_as_float(w[1] & 0xffff0000u)}; }
; __device__ __forceinline__ f32x4 bf_hi4(const u32x4& w) { return (f32x4){__uint_as_float(w[2] << 16), __uint_as_float(w[2] & 0xffff0000u), __uint_as_float(w[3] << 16), __uint_as_float(w[3] & 0xffff0000u)}; }
; __device__ __forceinline__ void epi_resid(bf16_t* XB, float* SS, float alpha, const f32x4 (&acc)[2][2][4][2], const Unit& u, int wr, int wc, int fr, int fq) {
;     ...
;     for (int it = 0; it < 8; ++it) {
;         const int ai = it >> 2, m = it & 3; const int r = opaque(EPI_ROW(it));
;         if (it + 1 < 8) { const bf16_t* p = XB + (size_t)opaque(EPI_ROW(it + 1)) * DM + c0; pre[(it + 1) & 1][0] = *(const u32x4*)p; pre[(it + 1) & 1][1] = *(const u32x4*)(p + 128); }
;         float q = 0.f;
; #pragma unroll
;         for (int bj = 0; bj < 2; ++bj) {
;             const size_t off = (size_t)r * DM + c0 + bj * 128;
;             const u32x4 bw = pre[it & 1][bj];
;             const f32x4 o0 = bf_lo4(bw) + acc[ai][bj][m][0] * alpha, o1 = bf_hi4(bw) + acc[ai][bj][m][1] * alpha;
;             u32x4 w; w[0] = pk2(o0[0], o0[1]); w[1] = pk2(o0[2], o0[3]); w[2] = pk2(o1[0], o1[1]); w[3] = pk2(o1[2], o1[3]);
;             *(u32x4*)(XB + off) = w;
;             q += (o0[0] * o0[0] + o0[1] * o0[1]) + (o0[2] * o0[2] + o0[3] * o0[3]) + (o1[0] * o1[0] + o1[1] * o1[1]) + (o1[2] * o1[2] + o1[3] * o1[3]);
;         }
;         q += __shfl_xor(q, 16); q += __shfl_xor(q, 32);
;         if (fq == 0) SS[(size_t)r * 32 + u.pn * 4 + wc] = q;
;         asm volatile("" ::: "memory");
;     }
; }
.LBB0_737:
	s_or_b64 exec, exec, s[12:13]
	v_add_u32_e32 v152, s14, v234
	v_mov_b32_e32 v138, v152
	s_waitcnt vmcnt(3)
	v_lshlrev_b32_e32 v154, 16, v134
	v_ashrrev_i32_e32 v139, 31, v138
	v_lshlrev_b64 v[138:139], 12, v[138:139]
	v_lshl_add_u64 v[138:139], v[150:151], 0, v[138:139]
	global_load_dwordx4 v[142:145], v[138:139], off
	s_waitcnt lgkmcnt(0)
	global_load_dwordx4 v[138:141], v[138:139], off offset:256
	v_and_b32_e32 v155, 0xffff0000, v134
	v_lshlrev_b32_e32 v134, 16, v135
	v_and_b32_e32 v135, 0xffff0000, v135
	v_ashrrev_i32_e32 v147, 31, v146
	v_pk_fma_f32 v[158:159], v[112:113], s[46:47], v[134:135]
	v_lshlrev_b32_e32 v134, 16, v136
	v_and_b32_e32 v135, 0xffff0000, v136
	v_lshlrev_b32_e32 v136, 16, v137
	v_and_b32_e32 v137, 0xffff0000, v137
	v_lshlrev_b64 v[148:149], 12, v[146:147]
	v_pk_fma_f32 v[154:155], v[110:111], s[40:41], v[154:155]
	v_pk_fma_f32 v[160:161], v[104:105], s[46:47], v[136:137]
	v_pk_fma_f32 v[162:163], v[102:103], s[40:41], v[134:135]
	v_lshl_add_u64 v[148:149], v[150:151], 0, v[148:149]
	v_cvt_pk_bf16_f32 v134, v154, v155
	v_cvt_pk_bf16_f32 v135, v158, v159
	v_cvt_pk_bf16_f32 v136, v162, v163
	v_cvt_pk_bf16_f32 v137, v160, v161
	global_store_dwordx4 v[148:149], v[134:137], off
	s_nop 1
	v_mul_f32_e32 v134, v155, v155
	v_mul_f32_e32 v135, v159, v159
	v_fmac_f32_e32 v134, v154, v154
	v_fmac_f32_e32 v135, v158, v158
	v_add_f32_e32 v134, v134, v135
	v_mul_f32_e32 v135, v163, v163
	v_fmac_f32_e32 v135, v162, v162
	v_add_f32_e32 v134, v135, v134
	v_mul_f32_e32 v135, v161, v161
	v_fmac_f32_e32 v135, v160, v160
	v_add_f32_e32 v153, v135, v134
	v_lshlrev_b32_e32 v134, 16, v130
	v_and_b32_e32 v135, 0xffff0000, v130
	v_lshlrev_b32_e32 v130, 16, v131
	v_and_b32_e32 v131, 0xffff0000, v131
	v_pk_fma_f32 v[136:137], v[108:109], s[46:47], v[130:131]
	v_lshlrev_b32_e32 v130, 16, v132
	v_and_b32_e32 v131, 0xffff0000, v132
	v_lshlrev_b32_e32 v132, 16, v133
	v_and_b32_e32 v133, 0xffff0000, v133
	v_pk_fma_f32 v[134:135], v[106:107], s[40:41], v[134:135]
	v_pk_fma_f32 v[154:155], v[100:101], s[46:47], v[132:133]
	v_pk_fma_f32 v[158:159], v[98:99], s[40:41], v[130:131]
	v_cvt_pk_bf16_f32 v130, v134, v135
	v_cvt_pk_bf16_f32 v131, v136, v137
	v_cvt_pk_bf16_f32 v132, v158, v159
	v_cvt_pk_bf16_f32 v133, v154, v155
	global_store_dwordx4 v[148:149], v[130:133], off offset:256
	s_nop 1
	v_mul_f32_e32 v130, v135, v135
	v_mul_f32_e32 v131, v137, v137
	v_fmac_f32_e32 v130, v134, v134
	v_fmac_f32_e32 v131, v136, v136
	v_add_f32_e32 v130, v130, v131
	v_mul_f32_e32 v131, v159, v159
	v_fmac_f32_e32 v131, v158, v158
	v_add_f32_e32 v130, v131, v130
	v_mul_f32_e32 v131, v155, v155
	v_fmac_f32_e32 v131, v154, v154
	v_add_f32_e32 v130, v131, v130
	v_add_f32_e32 v130, v153, v130
	ds_bpermute_b32 v131, v156, v130
	s_waitcnt lgkmcnt(0)
	v_add_f32_e32 v130, v130, v131
	ds_bpermute_b32 v131, v157, v130
	s_and_saveexec_b64 s[12:13], s[8:9]
	s_cbranch_execz .LBB0_739
	s_waitcnt lgkmcnt(0)
	v_add_f32_e32 v132, v130, v131
	s_lshl_b32 s16, s77, 2
	v_lshlrev_b64 v[130:131], 7, v[146:147]
	s_ashr_i32 s17, s16, 31
	v_lshl_add_u64 v[130:131], s[2:3], 0, v[130:131]
	v_lshl_add_u64 v[130:131], s[16:17], 2, v[130:131]
	s_lshl_b32 s36, s18, 2
	v_lshl_add_u64 v[130:131], v[130:131], 0, s[36:37]
	global_store_dword v[130:131], v132, off
.LBB0_739:
	s_or_b64 exec, exec, s[12:13]
	v_add_u32_e32 v154, s14, v235
	v_mov_b32_e32 v130, v154
	s_waitcnt vmcnt(3)
	v_lshlrev_b32_e32 v136, 16, v143
	s_waitcnt lgkmcnt(0)
	v_ashrrev_i32_e32 v131, 31, v130
	v_lshlrev_b64 v[130:131], 12, v[130:131]
	v_lshl_add_u64 v[130:131], v[150:151], 0, v[130:131]
	global_load_dwordx4 v[146:149], v[130:131], off
	s_nop 0
	global_load_dwordx4 v[130:133], v[130:131], off offset:256
	v_ashrrev_i32_e32 v153, 31, v152
	v_lshlrev_b64 v[134:135], 12, v[152:153]
	v_lshl_add_u64 v[158:159], v[150:151], 0, v[134:135]
	v_lshlrev_b32_e32 v134, 16, v142
	v_and_b32_e32 v135, 0xffff0000, v142
	v_and_b32_e32 v137, 0xffff0000, v143
	v_pk_fma_f32 v[142:143], v[96:97], s[46:47], v[136:137]
	v_pk_fma_f32 v[160:161], v[94:95], s[40:41], v[134:135]
	v_lshlrev_b32_e32 v134, 16, v144
	v_and_b32_e32 v135, 0xffff0000, v144
	v_lshlrev_b32_e32 v136, 16, v145
	v_and_b32_e32 v137, 0xffff0000, v145
	v_pk_fma_f32 v[144:145], v[88:89], s[46:47], v[136:137]
	v_pk_fma_f32 v[162:163], v[86:87], s[40:41], v[134:135]
	v_cvt_pk_bf16_f32 v134, v160, v161
	v_cvt_pk_bf16_f32 v135, v142, v143
	v_cvt_pk_bf16_f32 v136, v162, v163
	v_cvt_pk_bf16_f32 v137, v144, v145
	global_store_dwordx4 v[158:159], v[134:137], off
	s_nop 1
	v_mul_f32_e32 v134, v161, v161
	v_mul_f32_e32 v135, v143, v143
	v_fmac_f32_e32 v134, v160, v160
	v_fmac_f32_e32 v135, v142, v142
	v_add_f32_e32 v134, v134, v135
	v_mul_f32_e32 v135, v163, v163
	v_fmac_f32_e32 v135, v162, v162
	v_add_f32_e32 v134, v135, v134
	v_mul_f32_e32 v135, v145, v145
	v_fmac_f32_e32 v135, v144, v144
	v_add_f32_e32 v155, v135, v134
	v_lshlrev_b32_e32 v134, 16, v138
	v_and_b32_e32 v135, 0xffff0000, v138
	v_lshlrev_b32_e32 v136, 16, v139
	v_and_b32_e32 v137, 0xffff0000, v139
	v_pk_fma_f32 v[138:139], v[92:93], s[46:47], v[136:137]
	v_pk_fma_f32 v[142:143], v[90:91], s[40:41], v[134:135]
	v_lshlrev_b32_e32 v134, 16, v140
	v_and_b32_e32 v135, 0xffff0000, v140
	v_lshlrev_b32_e32 v136, 16, v141
	v_and_b32_e32 v137, 0xffff0000, v141
	v_pk_fma_f32 v[140:141], v[84:85], s[46:47], v[136:137]
	v_pk_fma_f32 v[144:145], v[82:83], s[40:41], v[134:135]
	v_cvt_pk_bf16_f32 v134, v142, v143
	v_cvt_pk_bf16_f32 v135, v138, v139
	v_cvt_pk_bf16_f32 v136, v144, v145
	v_cvt_pk_bf16_f32 v137, v140, v141
	global_store_dwordx4 v[158:159], v[134:137], off offset:256
	s_nop 1
	v_mul_f32_e32 v134, v143, v143
	v_mul_f32_e32 v135, v139, v139
	v_fmac_f32_e32 v134, v142, v142
	v_fmac_f32_e32 v135, v138, v138
	v_add_f32_e32 v134, v134, v135
	v_mul_f32_e32 v135, v145, v145
	v_fmac_f32_e32 v135, v144, v144
	v_add_f32_e32 v134, v135, v134
	v_mul_f32_e32 v135, v141, v141
	v_fmac_f32_e32 v135, v140, v140
	v_add_f32_e32 v134, v135, v134
	v_add_f32_e32 v134, v155, v134
	ds_bpermute_b32 v135, v156, v134
	s_waitcnt lgkmcnt(0)
	v_add_f32_e32 v134, v134, v135
	ds_bpermute_b32 v135, v157, v134
	s_and_saveexec_b64 s[12:13], s[8:9]
	s_cbranch_execz .LBB0_741
	s_waitcnt lgkmcnt(0)
	v_add_f32_e32 v136, v134, v135
	s_lshl_b32 s16, s77, 2
	v_lshlrev_b64 v[134:135], 7, v[152:153]
	s_ashr_i32 s17, s16, 31
	v_lshl_add_u64 v[134:135], s[2:3], 0, v[134:135]
	v_lshl_add_u64 v[134:135], s[16:17], 2, v[134:135]
	s_lshl_b32 s36, s18, 2
	v_lshl_add_u64 v[134:135], v[134:135], 0, s[36:37]
	global_store_dword v[134:135], v136, off
; __device__ __forceinline__ unsigned pk2(float lo, float hi) { f32x2 v = {lo, hi}; bf16x2_t b = __builtin_convertvector(v, bf16x2_t); return __builtin_bit_cast(unsigned, b); }
; __device__ __forceinline__ f32x4 bf_lo4(const u32x4& w) { return (f32x4){__uint_as_float(w[0] << 16), __uint_as_float(w[0] & 0xffff0000u), __uint_as_float(w[1] << 16), __uint_as_float(w[1] & 0xffff0000u)}; }
; __device__ __forceinline__ f32x4 bf_hi4(const u32x4& w) { return (f32x4){__uint_as_float(w[2] << 16), __uint_as_float(w[2] & 0xffff0000u), __uint_as_float(w[3] << 16), __uint_as_float(w[3] & 0xffff0000u)}; }
; __device__ __forceinline__ void epi_resid(bf16_t* XB, float* SS, float alpha, const f32x4 (&acc)[2][2][4][2], const Unit& u, int wr, int wc, int fr, int fq) {
;     ...
;     for (int it = 0; it < 8; ++it) {
;         const int ai = it >> 2, m = it & 3; const int r = opaque(EPI_ROW(it));
;         if (it + 1 < 8) { const bf16_t* p = XB + (size_t)opaque(EPI_ROW(it + 1)) * DM + c0; pre[(it + 1) & 1][0] = *(const u32x4*)p; pre[(it + 1) & 1][1] = *(const u32x4*)(p + 128); }
;         float q = 0.f;
; #pragma unroll
;         for (int bj = 0; bj < 2; ++bj) {
;             const size_t off = (size_t)r * DM + c0 + bj * 128;
;             const u32x4 bw = pre[it & 1][bj];
;             const f32x4 o0 = bf_lo4(bw) + acc[ai][bj][m][0] * alpha, o1 = bf_hi4(bw) + acc[ai][bj][m][1] * alpha;
;             u32x4 w; w[0] = pk2(o0[0], o0[1]); w[1] = pk2(o0[2], o0[3]); w[2] = pk2(o1[0], o1[1]); w[3] = pk2(o1[2], o1[3]);
;             *(u32x4*)(XB + off) = w;
;             q += (o0[0] * o0[0] + o0[1] * o0[1]) + (o0[2] * o0[2] + o0[3] * o0[3]) + (o1[0] * o1[0] + o1[1] * o1[1]) + (o1[2] * o1[2] + o1[3] * o1[3]);
;         }
;         q += __shfl_xor(q, 16); q += __shfl_xor(q, 32);
;         if (fq == 0) SS[(size_t)r * 32 + u.pn * 4 + wc] = q;
;         asm volatile("" ::: "memory");
;     }
; }
.LBB0_741:
	s_or_b64 exec, exec, s[12:13]
	v_add_u32_e32 v152, s14, v236
	v_mov_b32_e32 v134, v152
	s_waitcnt vmcnt(3)
	v_lshlrev_b32_e32 v144, 16, v147
	s_waitcnt lgkmcnt(0)
	v_ashrrev_i32_e32 v135, 31, v134
	v_lshlrev_b64 v[134:135], 12, v[134:135]
	v_lshl_add_u64 v[134:135], v[150:151], 0, v[134:135]
	global_load_dwordx4 v[138:141], v[134:135], off
	s_nop 0
	global_load_dwordx4 v[134:137], v[134:135], off offset:256
	v_ashrrev_i32_e32 v155, 31, v154
	v_lshlrev_b64 v[142:143], 12, v[154:155]
	v_lshl_add_u64 v[158:159], v[150:151], 0, v[142:143]
	v_lshlrev_b32_e32 v142, 16, v146
	v_and_b32_e32 v143, 0xffff0000, v146
	v_and_b32_e32 v145, 0xffff0000, v147
	v_pk_fma_f32 v[146:147], v[80:81], s[46:47], v[144:145]
	v_pk_fma_f32 v[160:161], v[78:79], s[40:41], v[142:143]
	v_lshlrev_b32_e32 v142, 16, v148
	v_and_b32_e32 v143, 0xffff0000, v148
	v_lshlrev_b32_e32 v144, 16, v149
	v_and_b32_e32 v145, 0xffff0000, v149
	v_pk_fma_f32 v[148:149], v[72:73], s[46:47], v[144:145]
	v_pk_fma_f32 v[162:163], v[70:71], s[40:41], v[142:143]
	v_cvt_pk_bf16_f32 v142, v160, v161
	v_cvt_pk_bf16_f32 v143, v146, v147
	v_cvt_pk_bf16_f32 v144, v162, v163
	v_cvt_pk_bf16_f32 v145, v148, v149
	global_store_dwordx4 v[158:159], v[142:145], off
	s_nop 1
	v_mul_f32_e32 v142, v161, v161
	v_mul_f32_e32 v143, v147, v147
	v_fmac_f32_e32 v142, v160, v160
	v_fmac_f32_e32 v143, v146, v146
	v_add_f32_e32 v142, v142, v143
	v_mul_f32_e32 v143, v163, v163
	v_fmac_f32_e32 v143, v162, v162
	v_add_f32_e32 v142, v143, v142
	v_mul_f32_e32 v143, v149, v149
	v_fmac_f32_e32 v143, v148, v148
	v_add_f32_e32 v153, v143, v142
	v_lshlrev_b32_e32 v142, 16, v130
	v_and_b32_e32 v143, 0xffff0000, v130
	v_lshlrev_b32_e32 v130, 16, v131
	v_and_b32_e32 v131, 0xffff0000, v131
	v_pk_fma_f32 v[144:145], v[76:77], s[46:47], v[130:131]
	v_lshlrev_b32_e32 v130, 16, v132
	v_and_b32_e32 v131, 0xffff0000, v132
	v_lshlrev_b32_e32 v132, 16, v133
	v_and_b32_e32 v133, 0xffff0000, v133
	v_pk_fma_f32 v[142:143], v[74:75], s[40:41], v[142:143]
	v_pk_fma_f32 v[146:147], v[68:69], s[46:47], v[132:133]
	v_pk_fma_f32 v[148:149], v[66:67], s[40:41], v[130:131]
	v_cvt_pk_bf16_f32 v130, v142, v143
	v_cvt_pk_bf16_f32 v131, v144, v145
	v_cvt_pk_bf16_f32 v132, v148, v149
	v_cvt_pk_bf16_f32 v133, v146, v147
	global_store_dwordx4 v[158:159], v[130:133], off offset:256
	s_nop 1
	v_mul_f32_e32 v130, v143, v143
	v_mul_f32_e32 v131, v145, v145
	v_fmac_f32_e32 v130, v142, v142
	v_fmac_f32_e32 v131, v144, v144
	v_add_f32_e32 v130, v130, v131
	v_mul_f32_e32 v131, v149, v149
	v_fmac_f32_e32 v131, v148, v148
	v_add_f32_e32 v130, v131, v130
	v_mul_f32_e32 v131, v147, v147
	v_fmac_f32_e32 v131, v146, v146
	v_add_f32_e32 v130, v131, v130
	v_add_f32_e32 v130, v153, v130
	ds_bpermute_b32 v131, v156, v130
	s_waitcnt lgkmcnt(0)
	v_add_f32_e32 v130, v130, v131
	ds_bpermute_b32 v131, v157, v130
	s_and_saveexec_b64 s[12:13], s[8:9]
	s_cbranch_execz .LBB0_743
	s_waitcnt lgkmcnt(0)
	v_add_f32_e32 v132, v130, v131
	s_lshl_b32 s16, s77, 2
	v_lshlrev_b64 v[130:131], 7, v[154:155]
	s_ashr_i32 s17, s16, 31
	v_lshl_add_u64 v[130:131], s[2:3], 0, v[130:131]
	v_lshl_add_u64 v[130:131], s[16:17], 2, v[130:131]
	s_lshl_b32 s36, s18, 2
	v_lshl_add_u64 v[130:131], v[130:131], 0, s[36:37]
	global_store_dword v[130:131], v132, off
.LBB0_743:
	s_or_b64 exec, exec, s[12:13]
	v_add_u32_e32 v146, s14, v237
	v_mov_b32_e32 v130, v146
	s_waitcnt vmcnt(3)
	v_lshlrev_b32_e32 v154, 16, v138
	s_waitcnt lgkmcnt(0)
	v_ashrrev_i32_e32 v131, 31, v130
	v_lshlrev_b64 v[130:131], 12, v[130:131]
	v_lshl_add_u64 v[130:131], v[150:151], 0, v[130:131]
	global_load_dwordx4 v[142:145], v[130:131], off
	s_nop 0
	global_load_dwordx4 v[130:133], v[130:131], off offset:256
	v_and_b32_e32 v155, 0xffff0000, v138
	v_lshlrev_b32_e32 v138, 16, v139
	v_and_b32_e32 v139, 0xffff0000, v139
	v_ashrrev_i32_e32 v153, 31, v152
	v_pk_fma_f32 v[158:159], v[64:65], s[46:47], v[138:139]
	v_lshlrev_b32_e32 v138, 16, v140
	v_and_b32_e32 v139, 0xffff0000, v140
	v_lshlrev_b32_e32 v140, 16, v141
	v_and_b32_e32 v141, 0xffff0000, v141
	v_lshlrev_b64 v[148:149], 12, v[152:153]
	v_pk_fma_f32 v[154:155], v[62:63], s[40:41], v[154:155]
	v_pk_fma_f32 v[160:161], v[56:57], s[46:47], v[140:141]
	v_pk_fma_f32 v[162:163], v[54:55], s[40:41], v[138:139]
	v_lshl_add_u64 v[148:149], v[150:151], 0, v[148:149]
	v_cvt_pk_bf16_f32 v138, v154, v155
	v_cvt_pk_bf16_f32 v139, v158, v159
	v_cvt_pk_bf16_f32 v140, v162, v163
	v_cvt_pk_bf16_f32 v141, v160, v161
	global_store_dwordx4 v[148:149], v[138:141], off
	s_nop 1
	v_mul_f32_e32 v138, v155, v155
	v_mul_f32_e32 v139, v159, v159
	v_fmac_f32_e32 v138, v154, v154
	v_fmac_f32_e32 v139, v158, v158
	v_add_f32_e32 v138, v138, v139
	v_mul_f32_e32 v139, v163, v163
	v_fmac_f32_e32 v139, v162, v162
	v_add_f32_e32 v138, v139, v138
	v_mul_f32_e32 v139, v161, v161
	v_fmac_f32_e32 v139, v160, v160
	v_add_f32_e32 v147, v139, v138
	v_lshlrev_b32_e32 v138, 16, v134
	v_and_b32_e32 v139, 0xffff0000, v134
	v_lshlrev_b32_e32 v134, 16, v135
	v_and_b32_e32 v135, 0xffff0000, v135
	v_pk_fma_f32 v[140:141], v[60:61], s[46:47], v[134:135]
	v_lshlrev_b32_e32 v134, 16, v136
	v_and_b32_e32 v135, 0xffff0000, v136
	v_lshlrev_b32_e32 v136, 16, v137
	v_and_b32_e32 v137, 0xffff0000, v137
	v_pk_fma_f32 v[138:139], v[58:59], s[40:41], v[138:139]
	v_pk_fma_f32 v[154:155], v[52:53], s[46:47], v[136:137]
	v_pk_fma_f32 v[158:159], v[50:51], s[40:41], v[134:135]
	v_cvt_pk_bf16_f32 v134, v138, v139
	v_cvt_pk_bf16_f32 v135, v140, v141
	v_cvt_pk_bf16_f32 v136, v158, v159
	v_cvt_pk_bf16_f32 v137, v154, v155
	global_store_dwordx4 v[148:149], v[134:137], off offset:256
	s_nop 1
	v_mul_f32_e32 v134, v139, v139
	v_mul_f32_e32 v135, v141, v141
	v_fmac_f32_e32 v134, v138, v138
	v_fmac_f32_e32 v135, v140, v140
	v_add_f32_e32 v134, v134, v135
	v_mul_f32_e32 v135, v159, v159
	v_fmac_f32_e32 v135, v158, v158
	v_add_f32_e32 v134, v135, v134
	v_mul_f32_e32 v135, v155, v155
	v_fmac_f32_e32 v135, v154, v154
	v_add_f32_e32 v134, v135, v134
	v_add_f32_e32 v134, v147, v134
	ds_bpermute_b32 v135, v156, v134
	s_waitcnt lgkmcnt(0)
	v_add_f32_e32 v134, v134, v135
	ds_bpermute_b32 v135, v157, v134
	s_and_saveexec_b64 s[12:13], s[8:9]
	s_cbranch_execz .LBB0_745
	s_waitcnt lgkmcnt(0)
	v_add_f32_e32 v136, v134, v135
	s_lshl_b32 s16, s77, 2
	v_lshlrev_b64 v[134:135], 7, v[152:153]
	s_ashr_i32 s17, s16, 31
	v_lshl_add_u64 v[134:135], s[2:3], 0, v[134:135]
	v_lshl_add_u64 v[134:135], s[16:17], 2, v[134:135]
	s_lshl_b32 s36, s18, 2
	v_lshl_add_u64 v[134:135], v[134:135], 0, s[36:37]
	global_store_dword v[134:135], v136, off
; __device__ __forceinline__ unsigned pk2(float lo, float hi) { f32x2 v = {lo, hi}; bf16x2_t b = __builtin_convertvector(v, bf16x2_t); return __builtin_bit_cast(unsigned, b); }
; __device__ __forceinline__ f32x4 bf_lo4(const u32x4& w) { return (f32x4){__uint_as_float(w[0] << 16), __uint_as_float(w[0] & 0xffff0000u), __uint_as_float(w[1] << 16), __uint_as_float(w[1] & 0xffff0000u)}; }
; __device__ __forceinline__ f32x4 bf_hi4(const u32x4& w) { return (f32x4){__uint_as_float(w[2] << 16), __uint_as_float(w[2] & 0xffff0000u), __uint_as_float(w[3] << 16), __uint_as_float(w[3] & 0xffff0000u)}; }
; __device__ __forceinline__ void epi_resid(bf16_t* XB, float* SS, float alpha, const f32x4 (&acc)[2][2][4][2], const Unit& u, int wr, int wc, int fr, int fq) {
;     ...
;     for (int it = 0; it < 8; ++it) {
;         const int ai = it >> 2, m = it & 3; const int r = opaque(EPI_ROW(it));
;         if (it + 1 < 8) { const bf16_t* p = XB + (size_t)opaque(EPI_ROW(it + 1)) * DM + c0; pre[(it + 1) & 1][0] = *(const u32x4*)p; pre[(it + 1) & 1][1] = *(const u32x4*)(p + 128); }
;         float q = 0.f;
; #pragma unroll
;         for (int bj = 0; bj < 2; ++bj) {
;             const size_t off = (size_t)r * DM + c0 + bj * 128;
;             const u32x4 bw = pre[it & 1][bj];
;             const f32x4 o0 = bf_lo4(bw) + acc[ai][bj][m][0] * alpha, o1 = bf_hi4(bw) + acc[ai][bj][m][1] * alpha;
;             u32x4 w; w[0] = pk2(o0[0], o0[1]); w[1] = pk2(o0[2], o0[3]); w[2] = pk2(o1[0], o1[1]); w[3] = pk2(o1[2], o1[3]);
;             *(u32x4*)(XB + off) = w;
;             q += (o0[0] * o0[0] + o0[1] * o0[1]) + (o0[2] * o0[2] + o0[3] * o0[3]) + (o1[0] * o1[0] + o1[1] * o1[1]) + (o1[2] * o1[2] + o1[3] * o1[3]);
;         }
;         q += __shfl_xor(q, 16); q += __shfl_xor(q, 32);
;         if (fq == 0) SS[(size_t)r * 32 + u.pn * 4 + wc] = q;
;         asm volatile("" ::: "memory");
;     }
; }
.LBB0_745:
	s_or_b64 exec, exec, s[12:13]
	v_add_u32_e32 v148, s14, v238
	v_mov_b32_e32 v134, v148
	s_waitcnt vmcnt(3)
	v_lshlrev_b32_e32 v154, 16, v142
	s_waitcnt lgkmcnt(0)
	v_ashrrev_i32_e32 v135, 31, v134
	v_lshlrev_b64 v[134:135], 12, v[134:135]
	v_lshl_add_u64 v[134:135], v[150:151], 0, v[134:135]
	global_load_dwordx4 v[138:141], v[134:135], off
	s_nop 0
	global_load_dwordx4 v[134:137], v[134:135], off offset:256
	v_and_b32_e32 v155, 0xffff0000, v142
	v_lshlrev_b32_e32 v142, 16, v143
	v_and_b32_e32 v143, 0xffff0000, v143
	v_ashrrev_i32_e32 v147, 31, v146
	v_pk_fma_f32 v[158:159], v[48:49], s[46:47], v[142:143]
	v_lshlrev_b32_e32 v142, 16, v144
	v_and_b32_e32 v143, 0xffff0000, v144
	v_lshlrev_b32_e32 v144, 16, v145
	v_and_b32_e32 v145, 0xffff0000, v145
	v_lshlrev_b64 v[152:153], 12, v[146:147]
	v_pk_fma_f32 v[154:155], v[46:47], s[40:41], v[154:155]
	v_pk_fma_f32 v[160:161], v[40:41], s[46:47], v[144:145]
	v_pk_fma_f32 v[162:163], v[38:39], s[40:41], v[142:143]
	v_lshl_add_u64 v[152:153], v[150:151], 0, v[152:153]
	v_cvt_pk_bf16_f32 v142, v154, v155
	v_cvt_pk_bf16_f32 v143, v158, v159
	v_cvt_pk_bf16_f32 v144, v162, v163
	v_cvt_pk_bf16_f32 v145, v160, v161
	global_store_dwordx4 v[152:153], v[142:145], off
	s_nop 1
	v_mul_f32_e32 v142, v155, v155
	v_mul_f32_e32 v143, v159, v159
	v_fmac_f32_e32 v142, v154, v154
	v_fmac_f32_e32 v143, v158, v158
	v_add_f32_e32 v142, v142, v143
	v_mul_f32_e32 v143, v163, v163
	v_fmac_f32_e32 v143, v162, v162
	v_add_f32_e32 v142, v143, v142
	v_mul_f32_e32 v143, v161, v161
	v_fmac_f32_e32 v143, v160, v160
	v_add_f32_e32 v149, v143, v142
	v_lshlrev_b32_e32 v142, 16, v130
	v_and_b32_e32 v143, 0xffff0000, v130
	v_lshlrev_b32_e32 v130, 16, v131
	v_and_b32_e32 v131, 0xffff0000, v131
	v_pk_fma_f32 v[144:145], v[44:45], s[46:47], v[130:131]
	v_lshlrev_b32_e32 v130, 16, v132
	v_and_b32_e32 v131, 0xffff0000, v132
	v_lshlrev_b32_e32 v132, 16, v133
	v_and_b32_e32 v133, 0xffff0000, v133
	v_pk_fma_f32 v[142:143], v[42:43], s[40:41], v[142:143]
	v_pk_fma_f32 v[154:155], v[36:37], s[46:47], v[132:133]
	v_pk_fma_f32 v[158:159], v[34:35], s[40:41], v[130:131]
	v_cvt_pk_bf16_f32 v130, v142, v143
	v_cvt_pk_bf16_f32 v131, v144, v145
	v_cvt_pk_bf16_f32 v132, v158, v159
	v_cvt_pk_bf16_f32 v133, v154, v155
	global_store_dwordx4 v[152:153], v[130:133], off offset:256
	s_nop 1
	v_mul_f32_e32 v130, v143, v143
	v_mul_f32_e32 v131, v145, v145
	v_fmac_f32_e32 v130, v142, v142
	v_fmac_f32_e32 v131, v144, v144
	v_add_f32_e32 v130, v130, v131
	v_mul_f32_e32 v131, v159, v159
	v_fmac_f32_e32 v131, v158, v158
	v_add_f32_e32 v130, v131, v130
	v_mul_f32_e32 v131, v155, v155
	v_fmac_f32_e32 v131, v154, v154
	v_add_f32_e32 v130, v131, v130
	v_add_f32_e32 v130, v149, v130
	ds_bpermute_b32 v131, v156, v130
	s_waitcnt lgkmcnt(0)
	v_add_f32_e32 v130, v130, v131
	ds_bpermute_b32 v131, v157, v130
	s_and_saveexec_b64 s[12:13], s[8:9]
	s_cbranch_execz .LBB0_747
	s_waitcnt lgkmcnt(0)
	v_add_f32_e32 v132, v130, v131
	s_lshl_b32 s16, s77, 2
	v_lshlrev_b64 v[130:131], 7, v[146:147]
	s_ashr_i32 s17, s16, 31
	v_lshl_add_u64 v[130:131], s[2:3], 0, v[130:131]
	v_lshl_add_u64 v[130:131], s[16:17], 2, v[130:131]
	s_lshl_b32 s36, s18, 2
	v_lshl_add_u64 v[130:131], v[130:131], 0, s[36:37]
	global_store_dword v[130:131], v132, off
; __device__ __forceinline__ unsigned pk2(float lo, float hi) { f32x2 v = {lo, hi}; bf16x2_t b = __builtin_convertvector(v, bf16x2_t); return __builtin_bit_cast(unsigned, b); }
; __device__ __forceinline__ f32x4 bf_lo4(const u32x4& w) { return (f32x4){__uint_as_float(w[0] << 16), __uint_as_float(w[0] & 0xffff0000u), __uint_as_float(w[1] << 16), __uint_as_float(w[1] & 0xffff0000u)}; }
; __device__ __forceinline__ f32x4 bf_hi4(const u32x4& w) { return (f32x4){__uint_as_float(w[2] << 16), __uint_as_float(w[2] & 0xffff0000u), __uint_as_float(w[3] << 16), __uint_as_float(w[3] & 0xffff0000u)}; }
; __device__ __forceinline__ void epi_resid(bf16_t* XB, float* SS, float alpha, const f32x4 (&acc)[2][2][4][2], const Unit& u, int wr, int wc, int fr, int fq) {
;     ...
;     for (int it = 0; it < 8; ++it) {
;         const int ai = it >> 2, m = it & 3; const int r = opaque(EPI_ROW(it));
;         if (it + 1 < 8) { const bf16_t* p = XB + (size_t)opaque(EPI_ROW(it + 1)) * DM + c0; pre[(it + 1) & 1][0] = *(const u32x4*)p; pre[(it + 1) & 1][1] = *(const u32x4*)(p + 128); }
;         float q = 0.f;
; #pragma unroll
;         for (int bj = 0; bj < 2; ++bj) {
;             const size_t off = (size_t)r * DM + c0 + bj * 128;
;             const u32x4 bw = pre[it & 1][bj];
;             const f32x4 o0 = bf_lo4(bw) + acc[ai][bj][m][0] * alpha, o1 = bf_hi4(bw) + acc[ai][bj][m][1] * alpha;
;             u32x4 w; w[0] = pk2(o0[0], o0[1]); w[1] = pk2(o0[2], o0[3]); w[2] = pk2(o1[0], o1[1]); w[3] = pk2(o1[2], o1[3]);
;             *(u32x4*)(XB + off) = w;
;             q += (o0[0] * o0[0] + o0[1] * o0[1]) + (o0[2] * o0[2] + o0[3] * o0[3]) + (o1[0] * o1[0] + o1[1] * o1[1]) + (o1[2] * o1[2] + o1[3] * o1[3]);
;         }
;         q += __shfl_xor(q, 16); q += __shfl_xor(q, 32);
;         if (fq == 0) SS[(size_t)r * 32 + u.pn * 4 + wc] = q;
;         asm volatile("" ::: "memory");
;     }
; }
.LBB0_747:
	s_or_b64 exec, exec, s[12:13]
	v_add_u32_e32 v146, s14, v239
	v_mov_b32_e32 v130, v146
	s_waitcnt vmcnt(3)
	v_lshlrev_b32_e32 v154, 16, v138
	s_waitcnt lgkmcnt(0)
	v_ashrrev_i32_e32 v131, 31, v130
	v_lshlrev_b64 v[130:131], 12, v[130:131]
	v_lshl_add_u64 v[130:131], v[150:151], 0, v[130:131]
	global_load_dwordx4 v[142:145], v[130:131], off
	s_nop 0
	global_load_dwordx4 v[130:133], v[130:131], off offset:256
	v_and_b32_e32 v155, 0xffff0000, v138
	v_lshlrev_b32_e32 v138, 16, v139
	v_and_b32_e32 v139, 0xffff0000, v139
	v_ashrrev_i32_e32 v149, 31, v148
	v_pk_fma_f32 v[158:159], v[32:33], s[46:47], v[138:139]
	v_lshlrev_b32_e32 v138, 16, v140
	v_and_b32_e32 v139, 0xffff0000, v140
	v_lshlrev_b32_e32 v140, 16, v141
	v_and_b32_e32 v141, 0xffff0000, v141
	v_lshlrev_b64 v[152:153], 12, v[148:149]
	v_pk_fma_f32 v[154:155], v[30:31], s[40:41], v[154:155]
	v_pk_fma_f32 v[160:161], v[24:25], s[46:47], v[140:141]
	v_pk_fma_f32 v[162:163], v[22:23], s[40:41], v[138:139]
	v_lshl_add_u64 v[152:153], v[150:151], 0, v[152:153]
	v_cvt_pk_bf16_f32 v138, v154, v155
	v_cvt_pk_bf16_f32 v139, v158, v159
	v_cvt_pk_bf16_f32 v140, v162, v163
	v_cvt_pk_bf16_f32 v141, v160, v161
	global_store_dwordx4 v[152:153], v[138:141], off
	s_nop 1
	v_mul_f32_e32 v138, v155, v155
	v_mul_f32_e32 v139, v159, v159
	v_fmac_f32_e32 v138, v154, v154
	v_fmac_f32_e32 v139, v158, v158
	v_add_f32_e32 v138, v138, v139
	v_mul_f32_e32 v139, v163, v163
	v_fmac_f32_e32 v139, v162, v162
	v_add_f32_e32 v138, v139, v138
	v_mul_f32_e32 v139, v161, v161
	v_fmac_f32_e32 v139, v160, v160
	v_add_f32_e32 v147, v139, v138
	v_lshlrev_b32_e32 v138, 16, v134
	v_and_b32_e32 v139, 0xffff0000, v134
	v_lshlrev_b32_e32 v134, 16, v135
	v_and_b32_e32 v135, 0xffff0000, v135
	v_pk_fma_f32 v[140:141], v[28:29], s[46:47], v[134:135]
	v_lshlrev_b32_e32 v134, 16, v136
	v_and_b32_e32 v135, 0xffff0000, v136
	v_lshlrev_b32_e32 v136, 16, v137
	v_and_b32_e32 v137, 0xffff0000, v137
	v_pk_fma_f32 v[138:139], v[26:27], s[40:41], v[138:139]
	v_pk_fma_f32 v[154:155], v[20:21], s[46:47], v[136:137]
	v_pk_fma_f32 v[158:159], v[18:19], s[40:41], v[134:135]
	v_cvt_pk_bf16_f32 v134, v138, v139
	v_cvt_pk_bf16_f32 v135, v140, v141
	v_cvt_pk_bf16_f32 v136, v158, v159
	v_cvt_pk_bf16_f32 v137, v154, v155
	global_store_dwordx4 v[152:153], v[134:137], off offset:256
	s_nop 1
	v_mul_f32_e32 v134, v139, v139
	v_mul_f32_e32 v135, v141, v141
	v_fmac_f32_e32 v134, v138, v138
	v_fmac_f32_e32 v135, v140, v140
	v_add_f32_e32 v134, v134, v135
	v_mul_f32_e32 v135, v159, v159
	v_fmac_f32_e32 v135, v158, v158
	v_add_f32_e32 v134, v135, v134
	v_mul_f32_e32 v135, v155, v155
	v_fmac_f32_e32 v135, v154, v154
	v_add_f32_e32 v134, v135, v134
	v_add_f32_e32 v134, v147, v134
	ds_bpermute_b32 v135, v156, v134
	s_waitcnt lgkmcnt(0)
	v_add_f32_e32 v134, v134, v135
	ds_bpermute_b32 v135, v157, v134
	s_and_saveexec_b64 s[12:13], s[8:9]
	s_cbranch_execz .LBB0_749
	s_waitcnt lgkmcnt(0)
	v_add_f32_e32 v136, v134, v135
	s_lshl_b32 s14, s77, 2
	v_lshlrev_b64 v[134:135], 7, v[148:149]
	s_ashr_i32 s15, s14, 31
	v_lshl_add_u64 v[134:135], s[2:3], 0, v[134:135]
	v_lshl_add_u64 v[134:135], s[14:15], 2, v[134:135]
	s_lshl_b32 s36, s18, 2
	v_lshl_add_u64 v[134:135], v[134:135], 0, s[36:37]
	global_store_dword v[134:135], v136, off
.LBB0_749:
	s_or_b64 exec, exec, s[12:13]
	s_waitcnt vmcnt(3)
	v_lshlrev_b32_e32 v136, 16, v143
	v_ashrrev_i32_e32 v147, 31, v146
	s_waitcnt lgkmcnt(0)
	v_lshlrev_b64 v[134:135], 12, v[146:147]
	v_lshl_add_u64 v[138:139], v[150:151], 0, v[134:135]
	v_lshlrev_b32_e32 v134, 16, v142
	v_and_b32_e32 v135, 0xffff0000, v142
	v_and_b32_e32 v137, 0xffff0000, v143
	v_pk_fma_f32 v[140:141], v[16:17], s[46:47], v[136:137]
	v_pk_fma_f32 v[142:143], v[14:15], s[40:41], v[134:135]
	v_lshlrev_b32_e32 v134, 16, v144
	v_and_b32_e32 v135, 0xffff0000, v144
	v_lshlrev_b32_e32 v136, 16, v145
	v_and_b32_e32 v137, 0xffff0000, v145
	v_pk_fma_f32 v[144:145], v[8:9], s[46:47], v[136:137]
	v_pk_fma_f32 v[148:149], v[6:7], s[40:41], v[134:135]
	v_cvt_pk_bf16_f32 v134, v142, v143
	v_cvt_pk_bf16_f32 v135, v140, v141
	v_cvt_pk_bf16_f32 v136, v148, v149
	v_cvt_pk_bf16_f32 v137, v144, v145
	global_store_dwordx4 v[138:139], v[134:137], off
	s_nop 1
	v_mul_f32_e32 v134, v143, v143
	v_mul_f32_e32 v135, v141, v141
	v_fmac_f32_e32 v134, v142, v142
	v_fmac_f32_e32 v135, v140, v140
	v_add_f32_e32 v134, v134, v135
	v_mul_f32_e32 v135, v149, v149
	v_fmac_f32_e32 v135, v148, v148
	v_add_f32_e32 v134, v135, v134
	v_mul_f32_e32 v135, v145, v145
	v_fmac_f32_e32 v135, v144, v144
	v_add_f32_e32 v144, v135, v134
	v_lshlrev_b32_e32 v134, 16, v130
	v_and_b32_e32 v135, 0xffff0000, v130
	v_lshlrev_b32_e32 v130, 16, v131
	v_and_b32_e32 v131, 0xffff0000, v131
	v_pk_fma_f32 v[136:137], v[12:13], s[46:47], v[130:131]
	v_lshlrev_b32_e32 v130, 16, v132
	v_and_b32_e32 v131, 0xffff0000, v132
	v_lshlrev_b32_e32 v132, 16, v133
	v_and_b32_e32 v133, 0xffff0000, v133
	v_pk_fma_f32 v[134:135], v[10:11], s[40:41], v[134:135]
	v_pk_fma_f32 v[140:141], v[4:5], s[46:47], v[132:133]
	v_pk_fma_f32 v[142:143], v[2:3], s[40:41], v[130:131]
	v_cvt_pk_bf16_f32 v130, v134, v135
	v_cvt_pk_bf16_f32 v131, v136, v137
	v_cvt_pk_bf16_f32 v132, v142, v143
	v_cvt_pk_bf16_f32 v133, v140, v141
	global_store_dwordx4 v[138:139], v[130:133], off offset:256
	s_nop 1
	v_mul_f32_e32 v130, v135, v135
	v_mul_f32_e32 v131, v137, v137
	v_fmac_f32_e32 v130, v134, v134
	v_fmac_f32_e32 v131, v136, v136
	v_add_f32_e32 v130, v130, v131
	v_mul_f32_e32 v131, v143, v143
	v_fmac_f32_e32 v131, v142, v142
	v_add_f32_e32 v130, v131, v130
	v_mul_f32_e32 v131, v141, v141
	v_fmac_f32_e32 v131, v140, v140
	v_add_f32_e32 v130, v131, v130
	v_add_f32_e32 v130, v144, v130
	ds_bpermute_b32 v131, v156, v130
	s_waitcnt lgkmcnt(0)
	v_add_f32_e32 v130, v130, v131
	ds_bpermute_b32 v131, v157, v130
	s_and_saveexec_b64 s[12:13], s[8:9]
	s_cbranch_execz .LBB0_751
	s_waitcnt lgkmcnt(0)
	v_add_f32_e32 v132, v130, v131
	s_lshl_b32 s14, s77, 2
	v_lshlrev_b64 v[130:131], 7, v[146:147]
	s_ashr_i32 s15, s14, 31
	v_lshl_add_u64 v[130:131], s[2:3], 0, v[130:131]
	v_lshl_add_u64 v[130:131], s[14:15], 2, v[130:131]
	s_lshl_b32 s36, s18, 2
	v_lshl_add_u64 v[130:131], v[130:131], 0, s[36:37]
	global_store_dword v[130:131], v132, off
